# phase-1 side jobs (layer-0 gemv + K/V pass, layer-1 gemv) assigned only to the 192 workgroups that run 8 instead of 9 GEMM tiles in that phase
# speedup vs baseline: 1.0018x; 1.0018x over previous
.LBB0_629:
	s_add_i32 s0, s93, s42
	s_lshr_b32 s1, s0, 31
	s_ashr_i32 s0, s0, 3
	s_add_i32 s0, s0, s1
	s_mul_i32 s0, s0, 15
	s_sub_i32 s33, s42, s0
	s_add_i32 s0, s42, 14
	s_mov_b64 s[2:3], -1
	s_mov_b64 s[10:11], 0
	s_cmp_gt_u32 s0, 28
	s_mov_b64 s[66:67], 0
	s_movk_i32 s25, 0x9ff
	s_mov_b32 s26, 0x1c000
	s_cbranch_scc0 .LBB0_658
	s_cmp_lt_i32 s33, 1
	s_mov_b64 s[0:1], -1
	s_cbranch_scc1 .LBB0_641
	s_cmp_eq_u32 s33, 1
	s_cbranch_scc0 .LBB0_640
	v_mov_b32_e32 v0, v216
	v_readlane_b32 s1, v249, 25
	v_readfirstlane_b32 s0, v0
	s_ashr_i32 s0, s0, 6
	s_add_i32 s2, s0, s1
	s_addk_i32 s2, 0xfe00
	s_cmp_lt_i32 s2, 0
	s_cselect_b32 s2, 0x7fff, s2
	s_cmpk_gt_i32 s2, 0x7f
	s_cbranch_scc1 .LBB0_640
	v_writelane_b32 v254, s33, 53
	v_writelane_b32 v254, s40, 38
	v_and_b32_e32 v10, 63, v0
	s_nop 0
	v_writelane_b32 v254, s41, 39
	v_writelane_b32 v254, s42, 40
	v_writelane_b32 v254, s43, 41
	s_branch .LBB0_635

.LBB0_819:
	s_andn2_b64 vcc, exec, s[10:11]
	s_cbranch_vccnz .LBB0_849
	s_cmp_gt_i32 s33, 0
	s_mov_b64 s[0:1], -1
	s_cbranch_scc0 .LBB0_836
	v_writelane_b32 v254, s33, 53
	v_mov_b32_e32 v0, v216
	v_writelane_b32 v254, s40, 38
	v_readlane_b32 s1, v249, 25
	v_readfirstlane_b32 s0, v0
	v_writelane_b32 v254, s41, 39
	s_ashr_i32 s0, s0, 6
	v_writelane_b32 v254, s42, 40
	s_add_i32 s2, s0, s1
	v_writelane_b32 v254, s43, 41
	s_addk_i32 s2, 0xfe00
	s_cmp_lt_i32 s2, 0
	s_cselect_b32 s2, 0x7fff, s2
	s_cmpk_gt_i32 s2, 0x707
	s_cbranch_scc1 .LBB0_828
	v_and_b32_e32 v10, 63, v0
	s_branch .LBB0_824
.LBB0_823:
	s_or_b64 exec, exec, s[0:1]
	v_readlane_b32 s0, v254, 6
	v_readlane_b32 s2, v254, 49
	s_addk_i32 s2, 0x600
	s_cmpk_lt_i32 s2, 0x708
	v_readlane_b32 s1, v254, 7
	s_cbranch_scc0 .LBB0_828

.LBB0_828:
	v_mov_b32_e32 v0, v216
	v_readlane_b32 s1, v249, 25
	v_readfirstlane_b32 s0, v0
	s_ashr_i32 s0, s0, 6
	s_add_i32 s2, s0, s1
	s_addk_i32 s2, 0xfe00
	s_cmp_lt_i32 s2, 0
	s_cselect_b32 s2, 0x7fff, s2
	v_readlane_b32 s20, v254, 24
	v_readlane_b32 s28, v254, 27
	v_readlane_b32 s82, v254, 34
	v_readlane_b32 s40, v254, 38
	v_readlane_b32 s60, v249, 14
	s_cmpk_gt_i32 s2, 0xfff
	v_readlane_b32 s21, v254, 25
	v_readlane_b32 s29, v254, 28
	s_mov_b32 s19, 0x400000
	s_movk_i32 s85, 0x1ff
	s_mov_b32 s92, 0x22000
	s_mov_b32 s80, 0x24000
	s_mov_b32 s36, 0x26000
	s_mov_b32 s84, 0x3e000
	v_readlane_b32 s83, v254, 35
	v_readlane_b32 s41, v254, 39
	v_readlane_b32 s42, v254, 40
	v_readlane_b32 s43, v254, 41
	s_mov_b32 s81, 0xfc000
	v_readlane_b32 s61, v249, 15
	s_cbranch_scc1 .LBB0_835
	s_waitcnt lgkmcnt(0)
	v_and_b32_e32 v2, 63, v0
	s_lshl_b32 s0, s0, 6
	v_readlane_b32 s1, v252, 37
	s_add_i32 s3, s1, s0
	s_add_i32 s3, s3, 0xffff8000
	v_lshlrev_b32_e32 v0, 2, v2
.LBB0_830:
	s_lshl_b32 s0, s3, 2
	s_and_b32 s5, s0, 0x1f00
	s_ashr_i32 s0, s2, 2
	s_lshr_b32 s4, s2, 2
	s_and_b32 s0, s0, 0xffffff80
	s_and_b32 s4, s4, 0x78
	s_ashr_i32 s1, s0, 31
	s_lshl_b32 s6, s4, 12
	v_readlane_b32 s7, v251, 30
	s_add_u32 s8, s7, s6
	v_readlane_b32 s6, v251, 31
	s_addc_u32 s9, s6, 0
	s_lshl_b64 s[6:7], s[0:1], 2
	s_add_u32 s6, s8, s6
	s_addc_u32 s7, s9, s7
	v_lshl_add_u64 v[4:5], s[6:7], 0, v[0:1]
	s_movk_i32 s1, 0x2000
	v_add_co_u32_e32 v6, vcc, s1, v4
	s_movk_i32 s1, 0x4000
	s_nop 0
	v_addc_co_u32_e32 v7, vcc, 0, v5, vcc
	global_load_dword v3, v0, s[6:7]
	global_load_dword v19, v[6:7], off offset:-4096
	global_load_dword v20, v[6:7], off
	v_add_co_u32_e32 v6, vcc, s1, v4
	s_movk_i32 s1, 0x5000
	s_nop 0
	v_addc_co_u32_e32 v7, vcc, 0, v5, vcc
	global_load_dword v21, v[6:7], off offset:-4096
	global_load_dword v22, v[6:7], off
	v_add_co_u32_e32 v6, vcc, s1, v4
	s_mul_hi_i32 s1, s0, 0xe0c0
	s_nop 0
	v_addc_co_u32_e32 v7, vcc, 0, v5, vcc
	global_load_dword v23, v[6:7], off
	v_add_co_u32_e32 v6, vcc, 0x6000, v4
	v_readlane_b32 s6, v254, 30
	s_nop 0
	v_addc_co_u32_e32 v7, vcc, 0, v5, vcc
	global_load_dword v24, v[6:7], off
	v_add_co_u32_e32 v6, vcc, 0x7000, v4
	v_readlane_b32 s7, v254, 31
	s_nop 0
	v_addc_co_u32_e32 v7, vcc, 0, v5, vcc
	global_load_dword v25, v[6:7], off
	v_lshl_or_b32 v6, v2, 2, s5
	s_mul_i32 s5, s0, 0xe0c0
	v_or_b32_e32 v6, s5, v6
	v_mov_b32_e32 v7, s1
	v_mov_b32_e32 v16, 0
	s_mov_b32 s0, 0
	v_lshl_add_u64 v[8:9], s[6:7], 0, v[6:7]
	v_mov_b32_e32 v17, v16
	v_mov_b32_e32 v14, v16
	v_mov_b32_e32 v15, v16
	v_mov_b32_e32 v12, v16
	v_mov_b32_e32 v13, v16
	v_mov_b32_e32 v10, v16
	v_mov_b32_e32 v11, v16
	s_mov_b32 s5, 0x2a000
	s_mov_b32 s14, 0x38000
	s_mov_b32 s15, 0x46000
	s_mov_b32 s16, 0x54000
	s_mov_b32 s17, 0x62000
	s_mov_b32 s18, 0xfff9e000
	s_mov_b32 s22, 0xfffac000
	s_mov_b32 s23, 0xfffba000
	s_mov_b32 s24, 0xfffc8000
	s_mov_b32 s25, 0xfffd6000
	s_mov_b32 s26, 0xfffe4000
	s_mov_b32 s27, 0xffff2000
	s_mov_b64 s[30:31], 0xe0c00
	s_mov_b32 s34, 0x1c000
	s_mov_b32 s35, 0xe000
	s_mov_b32 s16, 0x1000
	s_mov_b32 s17, 0
	v_mov_b32_e32 v34, v4
	v_mov_b32_e32 v35, v5
	global_load_dword v26, v[34:35], off offset:256
	v_lshl_add_u64 v[34:35], v[34:35], 0, s[16:17]
	global_load_dword v27, v[34:35], off offset:256
	v_lshl_add_u64 v[34:35], v[34:35], 0, s[16:17]
	global_load_dword v28, v[34:35], off offset:256
	v_lshl_add_u64 v[34:35], v[34:35], 0, s[16:17]
	global_load_dword v29, v[34:35], off offset:256
	v_lshl_add_u64 v[34:35], v[34:35], 0, s[16:17]
	global_load_dword v30, v[34:35], off offset:256
	v_lshl_add_u64 v[34:35], v[34:35], 0, s[16:17]
	global_load_dword v31, v[34:35], off offset:256
	v_lshl_add_u64 v[34:35], v[34:35], 0, s[16:17]
	global_load_dword v32, v[34:35], off offset:256
	v_lshl_add_u64 v[34:35], v[34:35], 0, s[16:17]
	global_load_dword v33, v[34:35], off offset:256
	s_mov_b32 s14, 0xfff8fa00
	s_mov_b32 s15, -1
	v_lshl_add_u64 v[8:9], v[8:9], 0, s[14:15]
	s_mov_b32 s14, 0xe0c0
	s_mov_b32 s15, 0
	global_load_dword v40, v[8:9], off
	v_lshl_add_u64 v[8:9], v[8:9], 0, s[14:15]
	global_load_dword v42, v[8:9], off
	v_lshl_add_u64 v[8:9], v[8:9], 0, s[14:15]
	global_load_dword v44, v[8:9], off
	v_lshl_add_u64 v[8:9], v[8:9], 0, s[14:15]
	global_load_dword v46, v[8:9], off
	v_lshl_add_u64 v[8:9], v[8:9], 0, s[14:15]
	global_load_dword v48, v[8:9], off
	v_lshl_add_u64 v[8:9], v[8:9], 0, s[14:15]
	global_load_dword v50, v[8:9], off
	v_lshl_add_u64 v[8:9], v[8:9], 0, s[14:15]
	global_load_dword v52, v[8:9], off
	v_lshl_add_u64 v[8:9], v[8:9], 0, s[14:15]
	global_load_dword v54, v[8:9], off
	v_lshl_add_u64 v[8:9], v[8:9], 0, s[14:15]
	global_load_dword v56, v[8:9], off
	v_lshl_add_u64 v[8:9], v[8:9], 0, s[14:15]
	global_load_dword v58, v[8:9], off
	v_lshl_add_u64 v[8:9], v[8:9], 0, s[14:15]
	global_load_dword v60, v[8:9], off
	v_lshl_add_u64 v[8:9], v[8:9], 0, s[14:15]
	global_load_dword v62, v[8:9], off
	v_lshl_add_u64 v[8:9], v[8:9], 0, s[14:15]
	global_load_dword v64, v[8:9], off
	v_lshl_add_u64 v[8:9], v[8:9], 0, s[14:15]
	global_load_dword v66, v[8:9], off
	v_lshl_add_u64 v[8:9], v[8:9], 0, s[14:15]
	global_load_dword v68, v[8:9], off
	v_lshl_add_u64 v[8:9], v[8:9], 0, s[14:15]
	global_load_dword v70, v[8:9], off
	v_lshl_add_u64 v[8:9], v[8:9], 0, s[14:15]
	global_load_dword v72, v[8:9], off
	v_lshl_add_u64 v[8:9], v[8:9], 0, s[14:15]
	global_load_dword v74, v[8:9], off
	v_lshl_add_u64 v[8:9], v[8:9], 0, s[14:15]
	global_load_dword v76, v[8:9], off
	v_lshl_add_u64 v[8:9], v[8:9], 0, s[14:15]
	global_load_dword v78, v[8:9], off
	v_lshl_add_u64 v[8:9], v[8:9], 0, s[14:15]
	global_load_dword v80, v[8:9], off
	v_lshl_add_u64 v[8:9], v[8:9], 0, s[14:15]
	global_load_dword v82, v[8:9], off
	v_lshl_add_u64 v[8:9], v[8:9], 0, s[14:15]
	global_load_dword v84, v[8:9], off
	v_lshl_add_u64 v[8:9], v[8:9], 0, s[14:15]
	global_load_dword v86, v[8:9], off
	v_lshl_add_u64 v[8:9], v[8:9], 0, s[14:15]
	global_load_dword v88, v[8:9], off
	v_lshl_add_u64 v[8:9], v[8:9], 0, s[14:15]
	global_load_dword v90, v[8:9], off
	v_lshl_add_u64 v[8:9], v[8:9], 0, s[14:15]
	global_load_dword v92, v[8:9], off
	v_lshl_add_u64 v[8:9], v[8:9], 0, s[14:15]
	global_load_dword v94, v[8:9], off
	v_lshl_add_u64 v[8:9], v[8:9], 0, s[14:15]
	global_load_dword v96, v[8:9], off
	v_lshl_add_u64 v[8:9], v[8:9], 0, s[14:15]
	global_load_dword v98, v[8:9], off
	v_lshl_add_u64 v[8:9], v[8:9], 0, s[14:15]
	global_load_dword v100, v[8:9], off
	v_lshl_add_u64 v[8:9], v[8:9], 0, s[14:15]
	global_load_dword v102, v[8:9], off
	v_lshl_add_u64 v[8:9], v[8:9], 0, s[14:15]
	global_load_dword v104, v[8:9], off
	v_lshl_add_u64 v[8:9], v[8:9], 0, s[14:15]
	global_load_dword v106, v[8:9], off
	v_lshl_add_u64 v[8:9], v[8:9], 0, s[14:15]
	global_load_dword v108, v[8:9], off
	v_lshl_add_u64 v[8:9], v[8:9], 0, s[14:15]
	global_load_dword v110, v[8:9], off
	v_lshl_add_u64 v[8:9], v[8:9], 0, s[14:15]
	global_load_dword v112, v[8:9], off
	v_lshl_add_u64 v[8:9], v[8:9], 0, s[14:15]
	global_load_dword v114, v[8:9], off
	v_lshl_add_u64 v[8:9], v[8:9], 0, s[14:15]
	global_load_dword v116, v[8:9], off
	v_lshl_add_u64 v[8:9], v[8:9], 0, s[14:15]
	global_load_dword v118, v[8:9], off
	v_lshl_add_u64 v[8:9], v[8:9], 0, s[14:15]
	global_load_dword v120, v[8:9], off
	v_lshl_add_u64 v[8:9], v[8:9], 0, s[14:15]
	global_load_dword v122, v[8:9], off
	v_lshl_add_u64 v[8:9], v[8:9], 0, s[14:15]
	global_load_dword v124, v[8:9], off
	v_lshl_add_u64 v[8:9], v[8:9], 0, s[14:15]
	global_load_dword v126, v[8:9], off
	v_lshl_add_u64 v[8:9], v[8:9], 0, s[14:15]
	global_load_dword v128, v[8:9], off
	v_lshl_add_u64 v[8:9], v[8:9], 0, s[14:15]
	global_load_dword v130, v[8:9], off
	v_lshl_add_u64 v[8:9], v[8:9], 0, s[14:15]
	global_load_dword v132, v[8:9], off
	v_lshl_add_u64 v[8:9], v[8:9], 0, s[14:15]
	global_load_dword v134, v[8:9], off
	v_lshl_add_u64 v[8:9], v[8:9], 0, s[14:15]
	global_load_dword v136, v[8:9], off
	v_lshl_add_u64 v[8:9], v[8:9], 0, s[14:15]
	global_load_dword v138, v[8:9], off
	v_lshl_add_u64 v[8:9], v[8:9], 0, s[14:15]
	global_load_dword v140, v[8:9], off
	v_lshl_add_u64 v[8:9], v[8:9], 0, s[14:15]
	global_load_dword v142, v[8:9], off
	v_lshl_add_u64 v[8:9], v[8:9], 0, s[14:15]
	global_load_dword v144, v[8:9], off
	v_lshl_add_u64 v[8:9], v[8:9], 0, s[14:15]
	global_load_dword v146, v[8:9], off
	v_lshl_add_u64 v[8:9], v[8:9], 0, s[14:15]
	global_load_dword v148, v[8:9], off
	v_lshl_add_u64 v[8:9], v[8:9], 0, s[14:15]
	global_load_dword v150, v[8:9], off
	v_lshl_add_u64 v[8:9], v[8:9], 0, s[14:15]
	global_load_dword v152, v[8:9], off
	v_lshl_add_u64 v[8:9], v[8:9], 0, s[14:15]
	global_load_dword v154, v[8:9], off
	v_lshl_add_u64 v[8:9], v[8:9], 0, s[14:15]
	global_load_dword v156, v[8:9], off
	v_lshl_add_u64 v[8:9], v[8:9], 0, s[14:15]
	global_load_dword v158, v[8:9], off
	v_lshl_add_u64 v[8:9], v[8:9], 0, s[14:15]
	global_load_dword v164, v[8:9], off
	v_lshl_add_u64 v[8:9], v[8:9], 0, s[14:15]
	global_load_dword v166, v[8:9], off
	v_lshl_add_u64 v[8:9], v[8:9], 0, s[14:15]
	global_load_dword v168, v[8:9], off
	v_lshl_add_u64 v[8:9], v[8:9], 0, s[14:15]
	global_load_dword v170, v[8:9], off
	s_waitcnt vmcnt(63)
	v_readlane_b32 s6, v3, 0
	v_readlane_b32 s7, v19, 0
	v_readlane_b32 s8, v20, 0
	v_readlane_b32 s9, v21, 0
	v_readlane_b32 s10, v22, 0
	v_readlane_b32 s11, v23, 0
	v_readlane_b32 s12, v24, 0
	v_readlane_b32 s13, v25, 0
	v_readlane_b32 s22, v3, 1
	v_readlane_b32 s23, v19, 1
	v_readlane_b32 s24, v20, 1
	v_readlane_b32 s25, v21, 1
	v_readlane_b32 s26, v22, 1
	v_readlane_b32 s27, v23, 1
	v_readlane_b32 s30, v24, 1
	v_readlane_b32 s31, v25, 1
	v_pk_fma_f32 v[16:17], v[40:41], s[6:7], v[16:17] op_sel_hi:[0,1,1]
	v_pk_fma_f32 v[14:15], v[40:41], s[8:9], v[14:15] op_sel_hi:[0,1,1]
	v_pk_fma_f32 v[12:13], v[40:41], s[10:11], v[12:13] op_sel_hi:[0,1,1]
	v_pk_fma_f32 v[10:11], v[40:41], s[12:13], v[10:11] op_sel_hi:[0,1,1]
	v_readlane_b32 s6, v3, 2
	v_readlane_b32 s7, v19, 2
	v_readlane_b32 s8, v20, 2
	v_readlane_b32 s9, v21, 2
	v_readlane_b32 s10, v22, 2
	v_readlane_b32 s11, v23, 2
	v_readlane_b32 s12, v24, 2
	v_readlane_b32 s13, v25, 2
	s_waitcnt vmcnt(62)
	v_pk_fma_f32 v[16:17], v[42:43], s[22:23], v[16:17] op_sel_hi:[0,1,1]
	v_pk_fma_f32 v[14:15], v[42:43], s[24:25], v[14:15] op_sel_hi:[0,1,1]
	v_pk_fma_f32 v[12:13], v[42:43], s[26:27], v[12:13] op_sel_hi:[0,1,1]
	v_pk_fma_f32 v[10:11], v[42:43], s[30:31], v[10:11] op_sel_hi:[0,1,1]
	v_readlane_b32 s22, v3, 3
	v_readlane_b32 s23, v19, 3
	v_readlane_b32 s24, v20, 3
	v_readlane_b32 s25, v21, 3
	v_readlane_b32 s26, v22, 3
	v_readlane_b32 s27, v23, 3
	v_readlane_b32 s30, v24, 3
	v_readlane_b32 s31, v25, 3
	s_waitcnt vmcnt(61)
	v_pk_fma_f32 v[16:17], v[44:45], s[6:7], v[16:17] op_sel_hi:[0,1,1]
	v_pk_fma_f32 v[14:15], v[44:45], s[8:9], v[14:15] op_sel_hi:[0,1,1]
	v_pk_fma_f32 v[12:13], v[44:45], s[10:11], v[12:13] op_sel_hi:[0,1,1]
	v_pk_fma_f32 v[10:11], v[44:45], s[12:13], v[10:11] op_sel_hi:[0,1,1]
	v_readlane_b32 s6, v3, 4
	v_readlane_b32 s7, v19, 4
	v_readlane_b32 s8, v20, 4
	v_readlane_b32 s9, v21, 4
	v_readlane_b32 s10, v22, 4
	v_readlane_b32 s11, v23, 4
	v_readlane_b32 s12, v24, 4
	v_readlane_b32 s13, v25, 4
	s_waitcnt vmcnt(60)
	v_pk_fma_f32 v[16:17], v[46:47], s[22:23], v[16:17] op_sel_hi:[0,1,1]
	v_pk_fma_f32 v[14:15], v[46:47], s[24:25], v[14:15] op_sel_hi:[0,1,1]
	v_pk_fma_f32 v[12:13], v[46:47], s[26:27], v[12:13] op_sel_hi:[0,1,1]
	v_pk_fma_f32 v[10:11], v[46:47], s[30:31], v[10:11] op_sel_hi:[0,1,1]
	v_readlane_b32 s22, v3, 5
	v_readlane_b32 s23, v19, 5
	v_readlane_b32 s24, v20, 5
	v_readlane_b32 s25, v21, 5
	v_readlane_b32 s26, v22, 5
	v_readlane_b32 s27, v23, 5
	v_readlane_b32 s30, v24, 5
	v_readlane_b32 s31, v25, 5
	s_waitcnt vmcnt(59)
	v_pk_fma_f32 v[16:17], v[48:49], s[6:7], v[16:17] op_sel_hi:[0,1,1]
	v_pk_fma_f32 v[14:15], v[48:49], s[8:9], v[14:15] op_sel_hi:[0,1,1]
	v_pk_fma_f32 v[12:13], v[48:49], s[10:11], v[12:13] op_sel_hi:[0,1,1]
	v_pk_fma_f32 v[10:11], v[48:49], s[12:13], v[10:11] op_sel_hi:[0,1,1]
	v_readlane_b32 s6, v3, 6
	v_readlane_b32 s7, v19, 6
	v_readlane_b32 s8, v20, 6
	v_readlane_b32 s9, v21, 6
	v_readlane_b32 s10, v22, 6
	v_readlane_b32 s11, v23, 6
	v_readlane_b32 s12, v24, 6
	v_readlane_b32 s13, v25, 6
	s_waitcnt vmcnt(58)
	v_pk_fma_f32 v[16:17], v[50:51], s[22:23], v[16:17] op_sel_hi:[0,1,1]
	v_pk_fma_f32 v[14:15], v[50:51], s[24:25], v[14:15] op_sel_hi:[0,1,1]
	v_pk_fma_f32 v[12:13], v[50:51], s[26:27], v[12:13] op_sel_hi:[0,1,1]
	v_pk_fma_f32 v[10:11], v[50:51], s[30:31], v[10:11] op_sel_hi:[0,1,1]
	v_readlane_b32 s22, v3, 7
	v_readlane_b32 s23, v19, 7
	v_readlane_b32 s24, v20, 7
	v_readlane_b32 s25, v21, 7
	v_readlane_b32 s26, v22, 7
	v_readlane_b32 s27, v23, 7
	v_readlane_b32 s30, v24, 7
	v_readlane_b32 s31, v25, 7
	s_waitcnt vmcnt(57)
	v_pk_fma_f32 v[16:17], v[52:53], s[6:7], v[16:17] op_sel_hi:[0,1,1]
	v_pk_fma_f32 v[14:15], v[52:53], s[8:9], v[14:15] op_sel_hi:[0,1,1]
	v_pk_fma_f32 v[12:13], v[52:53], s[10:11], v[12:13] op_sel_hi:[0,1,1]
	v_pk_fma_f32 v[10:11], v[52:53], s[12:13], v[10:11] op_sel_hi:[0,1,1]
	v_readlane_b32 s6, v3, 8
	v_readlane_b32 s7, v19, 8
	v_readlane_b32 s8, v20, 8
	v_readlane_b32 s9, v21, 8
	v_readlane_b32 s10, v22, 8
	v_readlane_b32 s11, v23, 8
	v_readlane_b32 s12, v24, 8
	v_readlane_b32 s13, v25, 8
	s_waitcnt vmcnt(56)
	v_pk_fma_f32 v[16:17], v[54:55], s[22:23], v[16:17] op_sel_hi:[0,1,1]
	v_pk_fma_f32 v[14:15], v[54:55], s[24:25], v[14:15] op_sel_hi:[0,1,1]
	v_pk_fma_f32 v[12:13], v[54:55], s[26:27], v[12:13] op_sel_hi:[0,1,1]
	v_pk_fma_f32 v[10:11], v[54:55], s[30:31], v[10:11] op_sel_hi:[0,1,1]
	v_readlane_b32 s22, v3, 9
	v_readlane_b32 s23, v19, 9
	v_readlane_b32 s24, v20, 9
	v_readlane_b32 s25, v21, 9
	v_readlane_b32 s26, v22, 9
	v_readlane_b32 s27, v23, 9
	v_readlane_b32 s30, v24, 9
	v_readlane_b32 s31, v25, 9
	s_waitcnt vmcnt(55)
	v_pk_fma_f32 v[16:17], v[56:57], s[6:7], v[16:17] op_sel_hi:[0,1,1]
	v_pk_fma_f32 v[14:15], v[56:57], s[8:9], v[14:15] op_sel_hi:[0,1,1]
	v_pk_fma_f32 v[12:13], v[56:57], s[10:11], v[12:13] op_sel_hi:[0,1,1]
	v_pk_fma_f32 v[10:11], v[56:57], s[12:13], v[10:11] op_sel_hi:[0,1,1]
	v_readlane_b32 s6, v3, 10
	v_readlane_b32 s7, v19, 10
	v_readlane_b32 s8, v20, 10
	v_readlane_b32 s9, v21, 10
	v_readlane_b32 s10, v22, 10
	v_readlane_b32 s11, v23, 10
	v_readlane_b32 s12, v24, 10
	v_readlane_b32 s13, v25, 10
	s_waitcnt vmcnt(54)
	v_pk_fma_f32 v[16:17], v[58:59], s[22:23], v[16:17] op_sel_hi:[0,1,1]
	v_pk_fma_f32 v[14:15], v[58:59], s[24:25], v[14:15] op_sel_hi:[0,1,1]
	v_pk_fma_f32 v[12:13], v[58:59], s[26:27], v[12:13] op_sel_hi:[0,1,1]
	v_pk_fma_f32 v[10:11], v[58:59], s[30:31], v[10:11] op_sel_hi:[0,1,1]
	v_readlane_b32 s22, v3, 11
	v_readlane_b32 s23, v19, 11
	v_readlane_b32 s24, v20, 11
	v_readlane_b32 s25, v21, 11
	v_readlane_b32 s26, v22, 11
	v_readlane_b32 s27, v23, 11
	v_readlane_b32 s30, v24, 11
	v_readlane_b32 s31, v25, 11
	s_waitcnt vmcnt(53)
	v_pk_fma_f32 v[16:17], v[60:61], s[6:7], v[16:17] op_sel_hi:[0,1,1]
	v_pk_fma_f32 v[14:15], v[60:61], s[8:9], v[14:15] op_sel_hi:[0,1,1]
	v_pk_fma_f32 v[12:13], v[60:61], s[10:11], v[12:13] op_sel_hi:[0,1,1]
	v_pk_fma_f32 v[10:11], v[60:61], s[12:13], v[10:11] op_sel_hi:[0,1,1]
	v_readlane_b32 s6, v3, 12
	v_readlane_b32 s7, v19, 12
	v_readlane_b32 s8, v20, 12
	v_readlane_b32 s9, v21, 12
	v_readlane_b32 s10, v22, 12
	v_readlane_b32 s11, v23, 12
	v_readlane_b32 s12, v24, 12
	v_readlane_b32 s13, v25, 12
	s_waitcnt vmcnt(52)
	v_pk_fma_f32 v[16:17], v[62:63], s[22:23], v[16:17] op_sel_hi:[0,1,1]
	v_pk_fma_f32 v[14:15], v[62:63], s[24:25], v[14:15] op_sel_hi:[0,1,1]
	v_pk_fma_f32 v[12:13], v[62:63], s[26:27], v[12:13] op_sel_hi:[0,1,1]
	v_pk_fma_f32 v[10:11], v[62:63], s[30:31], v[10:11] op_sel_hi:[0,1,1]
	v_readlane_b32 s22, v3, 13
	v_readlane_b32 s23, v19, 13
	v_readlane_b32 s24, v20, 13
	v_readlane_b32 s25, v21, 13
	v_readlane_b32 s26, v22, 13
	v_readlane_b32 s27, v23, 13
	v_readlane_b32 s30, v24, 13
	v_readlane_b32 s31, v25, 13
	s_waitcnt vmcnt(51)
	v_pk_fma_f32 v[16:17], v[64:65], s[6:7], v[16:17] op_sel_hi:[0,1,1]
	v_pk_fma_f32 v[14:15], v[64:65], s[8:9], v[14:15] op_sel_hi:[0,1,1]
	v_pk_fma_f32 v[12:13], v[64:65], s[10:11], v[12:13] op_sel_hi:[0,1,1]
	v_pk_fma_f32 v[10:11], v[64:65], s[12:13], v[10:11] op_sel_hi:[0,1,1]
	v_readlane_b32 s6, v3, 14
	v_readlane_b32 s7, v19, 14
	v_readlane_b32 s8, v20, 14
	v_readlane_b32 s9, v21, 14
	v_readlane_b32 s10, v22, 14
	v_readlane_b32 s11, v23, 14
	v_readlane_b32 s12, v24, 14
	v_readlane_b32 s13, v25, 14
	s_waitcnt vmcnt(50)
	v_pk_fma_f32 v[16:17], v[66:67], s[22:23], v[16:17] op_sel_hi:[0,1,1]
	v_pk_fma_f32 v[14:15], v[66:67], s[24:25], v[14:15] op_sel_hi:[0,1,1]
	v_pk_fma_f32 v[12:13], v[66:67], s[26:27], v[12:13] op_sel_hi:[0,1,1]
	v_pk_fma_f32 v[10:11], v[66:67], s[30:31], v[10:11] op_sel_hi:[0,1,1]
	v_readlane_b32 s22, v3, 15
	v_readlane_b32 s23, v19, 15
	v_readlane_b32 s24, v20, 15
	v_readlane_b32 s25, v21, 15
	v_readlane_b32 s26, v22, 15
	v_readlane_b32 s27, v23, 15
	v_readlane_b32 s30, v24, 15
	v_readlane_b32 s31, v25, 15
	s_waitcnt vmcnt(49)
	v_pk_fma_f32 v[16:17], v[68:69], s[6:7], v[16:17] op_sel_hi:[0,1,1]
	v_pk_fma_f32 v[14:15], v[68:69], s[8:9], v[14:15] op_sel_hi:[0,1,1]
	v_pk_fma_f32 v[12:13], v[68:69], s[10:11], v[12:13] op_sel_hi:[0,1,1]
	v_pk_fma_f32 v[10:11], v[68:69], s[12:13], v[10:11] op_sel_hi:[0,1,1]
	v_readlane_b32 s6, v3, 16
	v_readlane_b32 s7, v19, 16
	v_readlane_b32 s8, v20, 16
	v_readlane_b32 s9, v21, 16
	v_readlane_b32 s10, v22, 16
	v_readlane_b32 s11, v23, 16
	v_readlane_b32 s12, v24, 16
	v_readlane_b32 s13, v25, 16
	s_waitcnt vmcnt(48)
	v_pk_fma_f32 v[16:17], v[70:71], s[22:23], v[16:17] op_sel_hi:[0,1,1]
	v_pk_fma_f32 v[14:15], v[70:71], s[24:25], v[14:15] op_sel_hi:[0,1,1]
	v_pk_fma_f32 v[12:13], v[70:71], s[26:27], v[12:13] op_sel_hi:[0,1,1]
	v_pk_fma_f32 v[10:11], v[70:71], s[30:31], v[10:11] op_sel_hi:[0,1,1]
	v_readlane_b32 s22, v3, 17
	v_readlane_b32 s23, v19, 17
	v_readlane_b32 s24, v20, 17
	v_readlane_b32 s25, v21, 17
	v_readlane_b32 s26, v22, 17
	v_readlane_b32 s27, v23, 17
	v_readlane_b32 s30, v24, 17
	v_readlane_b32 s31, v25, 17
	s_waitcnt vmcnt(47)
	v_pk_fma_f32 v[16:17], v[72:73], s[6:7], v[16:17] op_sel_hi:[0,1,1]
	v_pk_fma_f32 v[14:15], v[72:73], s[8:9], v[14:15] op_sel_hi:[0,1,1]
	v_pk_fma_f32 v[12:13], v[72:73], s[10:11], v[12:13] op_sel_hi:[0,1,1]
	v_pk_fma_f32 v[10:11], v[72:73], s[12:13], v[10:11] op_sel_hi:[0,1,1]
	v_readlane_b32 s6, v3, 18
	v_readlane_b32 s7, v19, 18
	v_readlane_b32 s8, v20, 18
	v_readlane_b32 s9, v21, 18
	v_readlane_b32 s10, v22, 18
	v_readlane_b32 s11, v23, 18
	v_readlane_b32 s12, v24, 18
	v_readlane_b32 s13, v25, 18
	s_waitcnt vmcnt(46)
	v_pk_fma_f32 v[16:17], v[74:75], s[22:23], v[16:17] op_sel_hi:[0,1,1]
	v_pk_fma_f32 v[14:15], v[74:75], s[24:25], v[14:15] op_sel_hi:[0,1,1]
	v_pk_fma_f32 v[12:13], v[74:75], s[26:27], v[12:13] op_sel_hi:[0,1,1]
	v_pk_fma_f32 v[10:11], v[74:75], s[30:31], v[10:11] op_sel_hi:[0,1,1]
	v_readlane_b32 s22, v3, 19
	v_readlane_b32 s23, v19, 19
	v_readlane_b32 s24, v20, 19
	v_readlane_b32 s25, v21, 19
	v_readlane_b32 s26, v22, 19
	v_readlane_b32 s27, v23, 19
	v_readlane_b32 s30, v24, 19
	v_readlane_b32 s31, v25, 19
	s_waitcnt vmcnt(45)
	v_pk_fma_f32 v[16:17], v[76:77], s[6:7], v[16:17] op_sel_hi:[0,1,1]
	v_pk_fma_f32 v[14:15], v[76:77], s[8:9], v[14:15] op_sel_hi:[0,1,1]
	v_pk_fma_f32 v[12:13], v[76:77], s[10:11], v[12:13] op_sel_hi:[0,1,1]
	v_pk_fma_f32 v[10:11], v[76:77], s[12:13], v[10:11] op_sel_hi:[0,1,1]
	v_readlane_b32 s6, v3, 20
	v_readlane_b32 s7, v19, 20
	v_readlane_b32 s8, v20, 20
	v_readlane_b32 s9, v21, 20
	v_readlane_b32 s10, v22, 20
	v_readlane_b32 s11, v23, 20
	v_readlane_b32 s12, v24, 20
	v_readlane_b32 s13, v25, 20
	s_waitcnt vmcnt(44)
	v_pk_fma_f32 v[16:17], v[78:79], s[22:23], v[16:17] op_sel_hi:[0,1,1]
	v_pk_fma_f32 v[14:15], v[78:79], s[24:25], v[14:15] op_sel_hi:[0,1,1]
	v_pk_fma_f32 v[12:13], v[78:79], s[26:27], v[12:13] op_sel_hi:[0,1,1]
	v_pk_fma_f32 v[10:11], v[78:79], s[30:31], v[10:11] op_sel_hi:[0,1,1]
	v_readlane_b32 s22, v3, 21
	v_readlane_b32 s23, v19, 21
	v_readlane_b32 s24, v20, 21
	v_readlane_b32 s25, v21, 21
	v_readlane_b32 s26, v22, 21
	v_readlane_b32 s27, v23, 21
	v_readlane_b32 s30, v24, 21
	v_readlane_b32 s31, v25, 21
	s_waitcnt vmcnt(43)
	v_pk_fma_f32 v[16:17], v[80:81], s[6:7], v[16:17] op_sel_hi:[0,1,1]
	v_pk_fma_f32 v[14:15], v[80:81], s[8:9], v[14:15] op_sel_hi:[0,1,1]
	v_pk_fma_f32 v[12:13], v[80:81], s[10:11], v[12:13] op_sel_hi:[0,1,1]
	v_pk_fma_f32 v[10:11], v[80:81], s[12:13], v[10:11] op_sel_hi:[0,1,1]
	v_readlane_b32 s6, v3, 22
	v_readlane_b32 s7, v19, 22
	v_readlane_b32 s8, v20, 22
	v_readlane_b32 s9, v21, 22
	v_readlane_b32 s10, v22, 22
	v_readlane_b32 s11, v23, 22
	v_readlane_b32 s12, v24, 22
	v_readlane_b32 s13, v25, 22
	s_waitcnt vmcnt(42)
	v_pk_fma_f32 v[16:17], v[82:83], s[22:23], v[16:17] op_sel_hi:[0,1,1]
	v_pk_fma_f32 v[14:15], v[82:83], s[24:25], v[14:15] op_sel_hi:[0,1,1]
	v_pk_fma_f32 v[12:13], v[82:83], s[26:27], v[12:13] op_sel_hi:[0,1,1]
	v_pk_fma_f32 v[10:11], v[82:83], s[30:31], v[10:11] op_sel_hi:[0,1,1]
	v_readlane_b32 s22, v3, 23
	v_readlane_b32 s23, v19, 23
	v_readlane_b32 s24, v20, 23
	v_readlane_b32 s25, v21, 23
	v_readlane_b32 s26, v22, 23
	v_readlane_b32 s27, v23, 23
	v_readlane_b32 s30, v24, 23
	v_readlane_b32 s31, v25, 23
	s_waitcnt vmcnt(41)
	v_pk_fma_f32 v[16:17], v[84:85], s[6:7], v[16:17] op_sel_hi:[0,1,1]
	v_pk_fma_f32 v[14:15], v[84:85], s[8:9], v[14:15] op_sel_hi:[0,1,1]
	v_pk_fma_f32 v[12:13], v[84:85], s[10:11], v[12:13] op_sel_hi:[0,1,1]
	v_pk_fma_f32 v[10:11], v[84:85], s[12:13], v[10:11] op_sel_hi:[0,1,1]
	v_readlane_b32 s6, v3, 24
	v_readlane_b32 s7, v19, 24
	v_readlane_b32 s8, v20, 24
	v_readlane_b32 s9, v21, 24
	v_readlane_b32 s10, v22, 24
	v_readlane_b32 s11, v23, 24
	v_readlane_b32 s12, v24, 24
	v_readlane_b32 s13, v25, 24
	s_waitcnt vmcnt(40)
	v_pk_fma_f32 v[16:17], v[86:87], s[22:23], v[16:17] op_sel_hi:[0,1,1]
	v_pk_fma_f32 v[14:15], v[86:87], s[24:25], v[14:15] op_sel_hi:[0,1,1]
	v_pk_fma_f32 v[12:13], v[86:87], s[26:27], v[12:13] op_sel_hi:[0,1,1]
	v_pk_fma_f32 v[10:11], v[86:87], s[30:31], v[10:11] op_sel_hi:[0,1,1]
	v_readlane_b32 s22, v3, 25
	v_readlane_b32 s23, v19, 25
	v_readlane_b32 s24, v20, 25
	v_readlane_b32 s25, v21, 25
	v_readlane_b32 s26, v22, 25
	v_readlane_b32 s27, v23, 25
	v_readlane_b32 s30, v24, 25
	v_readlane_b32 s31, v25, 25
	s_waitcnt vmcnt(39)
	v_pk_fma_f32 v[16:17], v[88:89], s[6:7], v[16:17] op_sel_hi:[0,1,1]
	v_pk_fma_f32 v[14:15], v[88:89], s[8:9], v[14:15] op_sel_hi:[0,1,1]
	v_pk_fma_f32 v[12:13], v[88:89], s[10:11], v[12:13] op_sel_hi:[0,1,1]
	v_pk_fma_f32 v[10:11], v[88:89], s[12:13], v[10:11] op_sel_hi:[0,1,1]
	v_readlane_b32 s6, v3, 26
	v_readlane_b32 s7, v19, 26
	v_readlane_b32 s8, v20, 26
	v_readlane_b32 s9, v21, 26
	v_readlane_b32 s10, v22, 26
	v_readlane_b32 s11, v23, 26
	v_readlane_b32 s12, v24, 26
	v_readlane_b32 s13, v25, 26
	s_waitcnt vmcnt(38)
	v_pk_fma_f32 v[16:17], v[90:91], s[22:23], v[16:17] op_sel_hi:[0,1,1]
	v_pk_fma_f32 v[14:15], v[90:91], s[24:25], v[14:15] op_sel_hi:[0,1,1]
	v_pk_fma_f32 v[12:13], v[90:91], s[26:27], v[12:13] op_sel_hi:[0,1,1]
	v_pk_fma_f32 v[10:11], v[90:91], s[30:31], v[10:11] op_sel_hi:[0,1,1]
	v_readlane_b32 s22, v3, 27
	v_readlane_b32 s23, v19, 27
	v_readlane_b32 s24, v20, 27
	v_readlane_b32 s25, v21, 27
	v_readlane_b32 s26, v22, 27
	v_readlane_b32 s27, v23, 27
	v_readlane_b32 s30, v24, 27
	v_readlane_b32 s31, v25, 27
	s_waitcnt vmcnt(37)
	v_pk_fma_f32 v[16:17], v[92:93], s[6:7], v[16:17] op_sel_hi:[0,1,1]
	v_pk_fma_f32 v[14:15], v[92:93], s[8:9], v[14:15] op_sel_hi:[0,1,1]
	v_pk_fma_f32 v[12:13], v[92:93], s[10:11], v[12:13] op_sel_hi:[0,1,1]
	v_pk_fma_f32 v[10:11], v[92:93], s[12:13], v[10:11] op_sel_hi:[0,1,1]
	v_readlane_b32 s6, v3, 28
	v_readlane_b32 s7, v19, 28
	v_readlane_b32 s8, v20, 28
	v_readlane_b32 s9, v21, 28
	v_readlane_b32 s10, v22, 28
	v_readlane_b32 s11, v23, 28
	v_readlane_b32 s12, v24, 28
	v_readlane_b32 s13, v25, 28
	s_waitcnt vmcnt(36)
	v_pk_fma_f32 v[16:17], v[94:95], s[22:23], v[16:17] op_sel_hi:[0,1,1]
	v_pk_fma_f32 v[14:15], v[94:95], s[24:25], v[14:15] op_sel_hi:[0,1,1]
	v_pk_fma_f32 v[12:13], v[94:95], s[26:27], v[12:13] op_sel_hi:[0,1,1]
	v_pk_fma_f32 v[10:11], v[94:95], s[30:31], v[10:11] op_sel_hi:[0,1,1]
	v_readlane_b32 s22, v3, 29
	v_readlane_b32 s23, v19, 29
	v_readlane_b32 s24, v20, 29
	v_readlane_b32 s25, v21, 29
	v_readlane_b32 s26, v22, 29
	v_readlane_b32 s27, v23, 29
	v_readlane_b32 s30, v24, 29
	v_readlane_b32 s31, v25, 29
	s_waitcnt vmcnt(35)
	v_pk_fma_f32 v[16:17], v[96:97], s[6:7], v[16:17] op_sel_hi:[0,1,1]
	v_pk_fma_f32 v[14:15], v[96:97], s[8:9], v[14:15] op_sel_hi:[0,1,1]
	v_pk_fma_f32 v[12:13], v[96:97], s[10:11], v[12:13] op_sel_hi:[0,1,1]
	v_pk_fma_f32 v[10:11], v[96:97], s[12:13], v[10:11] op_sel_hi:[0,1,1]
	v_readlane_b32 s6, v3, 30
	v_readlane_b32 s7, v19, 30
	v_readlane_b32 s8, v20, 30
	v_readlane_b32 s9, v21, 30
	v_readlane_b32 s10, v22, 30
	v_readlane_b32 s11, v23, 30
	v_readlane_b32 s12, v24, 30
	v_readlane_b32 s13, v25, 30
	s_waitcnt vmcnt(34)
	v_pk_fma_f32 v[16:17], v[98:99], s[22:23], v[16:17] op_sel_hi:[0,1,1]
	v_pk_fma_f32 v[14:15], v[98:99], s[24:25], v[14:15] op_sel_hi:[0,1,1]
	v_pk_fma_f32 v[12:13], v[98:99], s[26:27], v[12:13] op_sel_hi:[0,1,1]
	v_pk_fma_f32 v[10:11], v[98:99], s[30:31], v[10:11] op_sel_hi:[0,1,1]
	v_readlane_b32 s22, v3, 31
	v_readlane_b32 s23, v19, 31
	v_readlane_b32 s24, v20, 31
	v_readlane_b32 s25, v21, 31
	v_readlane_b32 s26, v22, 31
	v_readlane_b32 s27, v23, 31
	v_readlane_b32 s30, v24, 31
	v_readlane_b32 s31, v25, 31
	s_waitcnt vmcnt(33)
	v_pk_fma_f32 v[16:17], v[100:101], s[6:7], v[16:17] op_sel_hi:[0,1,1]
	v_pk_fma_f32 v[14:15], v[100:101], s[8:9], v[14:15] op_sel_hi:[0,1,1]
	v_pk_fma_f32 v[12:13], v[100:101], s[10:11], v[12:13] op_sel_hi:[0,1,1]
	v_pk_fma_f32 v[10:11], v[100:101], s[12:13], v[10:11] op_sel_hi:[0,1,1]
	v_readlane_b32 s6, v3, 32
	v_readlane_b32 s7, v19, 32
	v_readlane_b32 s8, v20, 32
	v_readlane_b32 s9, v21, 32
	v_readlane_b32 s10, v22, 32
	v_readlane_b32 s11, v23, 32
	v_readlane_b32 s12, v24, 32
	v_readlane_b32 s13, v25, 32
	s_waitcnt vmcnt(32)
	v_pk_fma_f32 v[16:17], v[102:103], s[22:23], v[16:17] op_sel_hi:[0,1,1]
	v_pk_fma_f32 v[14:15], v[102:103], s[24:25], v[14:15] op_sel_hi:[0,1,1]
	v_pk_fma_f32 v[12:13], v[102:103], s[26:27], v[12:13] op_sel_hi:[0,1,1]
	v_pk_fma_f32 v[10:11], v[102:103], s[30:31], v[10:11] op_sel_hi:[0,1,1]
	v_readlane_b32 s22, v3, 33
	v_readlane_b32 s23, v19, 33
	v_readlane_b32 s24, v20, 33
	v_readlane_b32 s25, v21, 33
	v_readlane_b32 s26, v22, 33
	v_readlane_b32 s27, v23, 33
	v_readlane_b32 s30, v24, 33
	v_readlane_b32 s31, v25, 33
	s_waitcnt vmcnt(31)
	v_pk_fma_f32 v[16:17], v[104:105], s[6:7], v[16:17] op_sel_hi:[0,1,1]
	v_pk_fma_f32 v[14:15], v[104:105], s[8:9], v[14:15] op_sel_hi:[0,1,1]
	v_pk_fma_f32 v[12:13], v[104:105], s[10:11], v[12:13] op_sel_hi:[0,1,1]
	v_pk_fma_f32 v[10:11], v[104:105], s[12:13], v[10:11] op_sel_hi:[0,1,1]
	v_readlane_b32 s6, v3, 34
	v_readlane_b32 s7, v19, 34
	v_readlane_b32 s8, v20, 34
	v_readlane_b32 s9, v21, 34
	v_readlane_b32 s10, v22, 34
	v_readlane_b32 s11, v23, 34
	v_readlane_b32 s12, v24, 34
	v_readlane_b32 s13, v25, 34
	s_waitcnt vmcnt(30)
	v_pk_fma_f32 v[16:17], v[106:107], s[22:23], v[16:17] op_sel_hi:[0,1,1]
	v_pk_fma_f32 v[14:15], v[106:107], s[24:25], v[14:15] op_sel_hi:[0,1,1]
	v_pk_fma_f32 v[12:13], v[106:107], s[26:27], v[12:13] op_sel_hi:[0,1,1]
	v_pk_fma_f32 v[10:11], v[106:107], s[30:31], v[10:11] op_sel_hi:[0,1,1]
	v_readlane_b32 s22, v3, 35
	v_readlane_b32 s23, v19, 35
	v_readlane_b32 s24, v20, 35
	v_readlane_b32 s25, v21, 35
	v_readlane_b32 s26, v22, 35
	v_readlane_b32 s27, v23, 35
	v_readlane_b32 s30, v24, 35
	v_readlane_b32 s31, v25, 35
	s_waitcnt vmcnt(29)
	v_pk_fma_f32 v[16:17], v[108:109], s[6:7], v[16:17] op_sel_hi:[0,1,1]
	v_pk_fma_f32 v[14:15], v[108:109], s[8:9], v[14:15] op_sel_hi:[0,1,1]
	v_pk_fma_f32 v[12:13], v[108:109], s[10:11], v[12:13] op_sel_hi:[0,1,1]
	v_pk_fma_f32 v[10:11], v[108:109], s[12:13], v[10:11] op_sel_hi:[0,1,1]
	v_readlane_b32 s6, v3, 36
	v_readlane_b32 s7, v19, 36
	v_readlane_b32 s8, v20, 36
	v_readlane_b32 s9, v21, 36
	v_readlane_b32 s10, v22, 36
	v_readlane_b32 s11, v23, 36
	v_readlane_b32 s12, v24, 36
	v_readlane_b32 s13, v25, 36
	s_waitcnt vmcnt(28)
	v_pk_fma_f32 v[16:17], v[110:111], s[22:23], v[16:17] op_sel_hi:[0,1,1]
	v_pk_fma_f32 v[14:15], v[110:111], s[24:25], v[14:15] op_sel_hi:[0,1,1]
	v_pk_fma_f32 v[12:13], v[110:111], s[26:27], v[12:13] op_sel_hi:[0,1,1]
	v_pk_fma_f32 v[10:11], v[110:111], s[30:31], v[10:11] op_sel_hi:[0,1,1]
	v_readlane_b32 s22, v3, 37
	v_readlane_b32 s23, v19, 37
	v_readlane_b32 s24, v20, 37
	v_readlane_b32 s25, v21, 37
	v_readlane_b32 s26, v22, 37
	v_readlane_b32 s27, v23, 37
	v_readlane_b32 s30, v24, 37
	v_readlane_b32 s31, v25, 37
	s_waitcnt vmcnt(27)
	v_pk_fma_f32 v[16:17], v[112:113], s[6:7], v[16:17] op_sel_hi:[0,1,1]
	v_pk_fma_f32 v[14:15], v[112:113], s[8:9], v[14:15] op_sel_hi:[0,1,1]
	v_pk_fma_f32 v[12:13], v[112:113], s[10:11], v[12:13] op_sel_hi:[0,1,1]
	v_pk_fma_f32 v[10:11], v[112:113], s[12:13], v[10:11] op_sel_hi:[0,1,1]
	v_readlane_b32 s6, v3, 38
	v_readlane_b32 s7, v19, 38
	v_readlane_b32 s8, v20, 38
	v_readlane_b32 s9, v21, 38
	v_readlane_b32 s10, v22, 38
	v_readlane_b32 s11, v23, 38
	v_readlane_b32 s12, v24, 38
	v_readlane_b32 s13, v25, 38
	s_waitcnt vmcnt(26)
	v_pk_fma_f32 v[16:17], v[114:115], s[22:23], v[16:17] op_sel_hi:[0,1,1]
	v_pk_fma_f32 v[14:15], v[114:115], s[24:25], v[14:15] op_sel_hi:[0,1,1]
	v_pk_fma_f32 v[12:13], v[114:115], s[26:27], v[12:13] op_sel_hi:[0,1,1]
	v_pk_fma_f32 v[10:11], v[114:115], s[30:31], v[10:11] op_sel_hi:[0,1,1]
	v_readlane_b32 s22, v3, 39
	v_readlane_b32 s23, v19, 39
	v_readlane_b32 s24, v20, 39
	v_readlane_b32 s25, v21, 39
	v_readlane_b32 s26, v22, 39
	v_readlane_b32 s27, v23, 39
	v_readlane_b32 s30, v24, 39
	v_readlane_b32 s31, v25, 39
	s_waitcnt vmcnt(25)
	v_pk_fma_f32 v[16:17], v[116:117], s[6:7], v[16:17] op_sel_hi:[0,1,1]
	v_pk_fma_f32 v[14:15], v[116:117], s[8:9], v[14:15] op_sel_hi:[0,1,1]
	v_pk_fma_f32 v[12:13], v[116:117], s[10:11], v[12:13] op_sel_hi:[0,1,1]
	v_pk_fma_f32 v[10:11], v[116:117], s[12:13], v[10:11] op_sel_hi:[0,1,1]
	v_readlane_b32 s6, v3, 40
	v_readlane_b32 s7, v19, 40
	v_readlane_b32 s8, v20, 40
	v_readlane_b32 s9, v21, 40
	v_readlane_b32 s10, v22, 40
	v_readlane_b32 s11, v23, 40
	v_readlane_b32 s12, v24, 40
	v_readlane_b32 s13, v25, 40
	s_waitcnt vmcnt(24)
	v_pk_fma_f32 v[16:17], v[118:119], s[22:23], v[16:17] op_sel_hi:[0,1,1]
	v_pk_fma_f32 v[14:15], v[118:119], s[24:25], v[14:15] op_sel_hi:[0,1,1]
	v_pk_fma_f32 v[12:13], v[118:119], s[26:27], v[12:13] op_sel_hi:[0,1,1]
	v_pk_fma_f32 v[10:11], v[118:119], s[30:31], v[10:11] op_sel_hi:[0,1,1]
	v_readlane_b32 s22, v3, 41
	v_readlane_b32 s23, v19, 41
	v_readlane_b32 s24, v20, 41
	v_readlane_b32 s25, v21, 41
	v_readlane_b32 s26, v22, 41
	v_readlane_b32 s27, v23, 41
	v_readlane_b32 s30, v24, 41
	v_readlane_b32 s31, v25, 41
	s_waitcnt vmcnt(23)
	v_pk_fma_f32 v[16:17], v[120:121], s[6:7], v[16:17] op_sel_hi:[0,1,1]
	v_pk_fma_f32 v[14:15], v[120:121], s[8:9], v[14:15] op_sel_hi:[0,1,1]
	v_pk_fma_f32 v[12:13], v[120:121], s[10:11], v[12:13] op_sel_hi:[0,1,1]
	v_pk_fma_f32 v[10:11], v[120:121], s[12:13], v[10:11] op_sel_hi:[0,1,1]
	v_readlane_b32 s6, v3, 42
	v_readlane_b32 s7, v19, 42
	v_readlane_b32 s8, v20, 42
	v_readlane_b32 s9, v21, 42
	v_readlane_b32 s10, v22, 42
	v_readlane_b32 s11, v23, 42
	v_readlane_b32 s12, v24, 42
	v_readlane_b32 s13, v25, 42
	s_waitcnt vmcnt(22)
	v_pk_fma_f32 v[16:17], v[122:123], s[22:23], v[16:17] op_sel_hi:[0,1,1]
	v_pk_fma_f32 v[14:15], v[122:123], s[24:25], v[14:15] op_sel_hi:[0,1,1]
	v_pk_fma_f32 v[12:13], v[122:123], s[26:27], v[12:13] op_sel_hi:[0,1,1]
	v_pk_fma_f32 v[10:11], v[122:123], s[30:31], v[10:11] op_sel_hi:[0,1,1]
	v_readlane_b32 s22, v3, 43
	v_readlane_b32 s23, v19, 43
	v_readlane_b32 s24, v20, 43
	v_readlane_b32 s25, v21, 43
	v_readlane_b32 s26, v22, 43
	v_readlane_b32 s27, v23, 43
	v_readlane_b32 s30, v24, 43
	v_readlane_b32 s31, v25, 43
	s_waitcnt vmcnt(21)
	v_pk_fma_f32 v[16:17], v[124:125], s[6:7], v[16:17] op_sel_hi:[0,1,1]
	v_pk_fma_f32 v[14:15], v[124:125], s[8:9], v[14:15] op_sel_hi:[0,1,1]
	v_pk_fma_f32 v[12:13], v[124:125], s[10:11], v[12:13] op_sel_hi:[0,1,1]
	v_pk_fma_f32 v[10:11], v[124:125], s[12:13], v[10:11] op_sel_hi:[0,1,1]
	v_readlane_b32 s6, v3, 44
	v_readlane_b32 s7, v19, 44
	v_readlane_b32 s8, v20, 44
	v_readlane_b32 s9, v21, 44
	v_readlane_b32 s10, v22, 44
	v_readlane_b32 s11, v23, 44
	v_readlane_b32 s12, v24, 44
	v_readlane_b32 s13, v25, 44
	s_waitcnt vmcnt(20)
	v_pk_fma_f32 v[16:17], v[126:127], s[22:23], v[16:17] op_sel_hi:[0,1,1]
	v_pk_fma_f32 v[14:15], v[126:127], s[24:25], v[14:15] op_sel_hi:[0,1,1]
	v_pk_fma_f32 v[12:13], v[126:127], s[26:27], v[12:13] op_sel_hi:[0,1,1]
	v_pk_fma_f32 v[10:11], v[126:127], s[30:31], v[10:11] op_sel_hi:[0,1,1]
	v_readlane_b32 s22, v3, 45
	v_readlane_b32 s23, v19, 45
	v_readlane_b32 s24, v20, 45
	v_readlane_b32 s25, v21, 45
	v_readlane_b32 s26, v22, 45
	v_readlane_b32 s27, v23, 45
	v_readlane_b32 s30, v24, 45
	v_readlane_b32 s31, v25, 45
	s_waitcnt vmcnt(19)
	v_pk_fma_f32 v[16:17], v[128:129], s[6:7], v[16:17] op_sel_hi:[0,1,1]
	v_pk_fma_f32 v[14:15], v[128:129], s[8:9], v[14:15] op_sel_hi:[0,1,1]
	v_pk_fma_f32 v[12:13], v[128:129], s[10:11], v[12:13] op_sel_hi:[0,1,1]
	v_pk_fma_f32 v[10:11], v[128:129], s[12:13], v[10:11] op_sel_hi:[0,1,1]
	v_readlane_b32 s6, v3, 46
	v_readlane_b32 s7, v19, 46
	v_readlane_b32 s8, v20, 46
	v_readlane_b32 s9, v21, 46
	v_readlane_b32 s10, v22, 46
	v_readlane_b32 s11, v23, 46
	v_readlane_b32 s12, v24, 46
	v_readlane_b32 s13, v25, 46
	s_waitcnt vmcnt(18)
	v_pk_fma_f32 v[16:17], v[130:131], s[22:23], v[16:17] op_sel_hi:[0,1,1]
	v_pk_fma_f32 v[14:15], v[130:131], s[24:25], v[14:15] op_sel_hi:[0,1,1]
	v_pk_fma_f32 v[12:13], v[130:131], s[26:27], v[12:13] op_sel_hi:[0,1,1]
	v_pk_fma_f32 v[10:11], v[130:131], s[30:31], v[10:11] op_sel_hi:[0,1,1]
	v_readlane_b32 s22, v3, 47
	v_readlane_b32 s23, v19, 47
	v_readlane_b32 s24, v20, 47
	v_readlane_b32 s25, v21, 47
	v_readlane_b32 s26, v22, 47
	v_readlane_b32 s27, v23, 47
	v_readlane_b32 s30, v24, 47
	v_readlane_b32 s31, v25, 47
	s_waitcnt vmcnt(17)
	v_pk_fma_f32 v[16:17], v[132:133], s[6:7], v[16:17] op_sel_hi:[0,1,1]
	v_pk_fma_f32 v[14:15], v[132:133], s[8:9], v[14:15] op_sel_hi:[0,1,1]
	v_pk_fma_f32 v[12:13], v[132:133], s[10:11], v[12:13] op_sel_hi:[0,1,1]
	v_pk_fma_f32 v[10:11], v[132:133], s[12:13], v[10:11] op_sel_hi:[0,1,1]
	v_readlane_b32 s6, v3, 48
	v_readlane_b32 s7, v19, 48
	v_readlane_b32 s8, v20, 48
	v_readlane_b32 s9, v21, 48
	v_readlane_b32 s10, v22, 48
	v_readlane_b32 s11, v23, 48
	v_readlane_b32 s12, v24, 48
	v_readlane_b32 s13, v25, 48
	s_waitcnt vmcnt(16)
	v_pk_fma_f32 v[16:17], v[134:135], s[22:23], v[16:17] op_sel_hi:[0,1,1]
	v_pk_fma_f32 v[14:15], v[134:135], s[24:25], v[14:15] op_sel_hi:[0,1,1]
	v_pk_fma_f32 v[12:13], v[134:135], s[26:27], v[12:13] op_sel_hi:[0,1,1]
	v_pk_fma_f32 v[10:11], v[134:135], s[30:31], v[10:11] op_sel_hi:[0,1,1]
	v_readlane_b32 s22, v3, 49
	v_readlane_b32 s23, v19, 49
	v_readlane_b32 s24, v20, 49
	v_readlane_b32 s25, v21, 49
	v_readlane_b32 s26, v22, 49
	v_readlane_b32 s27, v23, 49
	v_readlane_b32 s30, v24, 49
	v_readlane_b32 s31, v25, 49
	s_waitcnt vmcnt(15)
	v_pk_fma_f32 v[16:17], v[136:137], s[6:7], v[16:17] op_sel_hi:[0,1,1]
	v_pk_fma_f32 v[14:15], v[136:137], s[8:9], v[14:15] op_sel_hi:[0,1,1]
	v_pk_fma_f32 v[12:13], v[136:137], s[10:11], v[12:13] op_sel_hi:[0,1,1]
	v_pk_fma_f32 v[10:11], v[136:137], s[12:13], v[10:11] op_sel_hi:[0,1,1]
	v_readlane_b32 s6, v3, 50
	v_readlane_b32 s7, v19, 50
	v_readlane_b32 s8, v20, 50
	v_readlane_b32 s9, v21, 50
	v_readlane_b32 s10, v22, 50
	v_readlane_b32 s11, v23, 50
	v_readlane_b32 s12, v24, 50
	v_readlane_b32 s13, v25, 50
	s_waitcnt vmcnt(14)
	v_pk_fma_f32 v[16:17], v[138:139], s[22:23], v[16:17] op_sel_hi:[0,1,1]
	v_pk_fma_f32 v[14:15], v[138:139], s[24:25], v[14:15] op_sel_hi:[0,1,1]
	v_pk_fma_f32 v[12:13], v[138:139], s[26:27], v[12:13] op_sel_hi:[0,1,1]
	v_pk_fma_f32 v[10:11], v[138:139], s[30:31], v[10:11] op_sel_hi:[0,1,1]
	v_readlane_b32 s22, v3, 51
	v_readlane_b32 s23, v19, 51
	v_readlane_b32 s24, v20, 51
	v_readlane_b32 s25, v21, 51
	v_readlane_b32 s26, v22, 51
	v_readlane_b32 s27, v23, 51
	v_readlane_b32 s30, v24, 51
	v_readlane_b32 s31, v25, 51
	s_waitcnt vmcnt(13)
	v_pk_fma_f32 v[16:17], v[140:141], s[6:7], v[16:17] op_sel_hi:[0,1,1]
	v_pk_fma_f32 v[14:15], v[140:141], s[8:9], v[14:15] op_sel_hi:[0,1,1]
	v_pk_fma_f32 v[12:13], v[140:141], s[10:11], v[12:13] op_sel_hi:[0,1,1]
	v_pk_fma_f32 v[10:11], v[140:141], s[12:13], v[10:11] op_sel_hi:[0,1,1]
	v_readlane_b32 s6, v3, 52
	v_readlane_b32 s7, v19, 52
	v_readlane_b32 s8, v20, 52
	v_readlane_b32 s9, v21, 52
	v_readlane_b32 s10, v22, 52
	v_readlane_b32 s11, v23, 52
	v_readlane_b32 s12, v24, 52
	v_readlane_b32 s13, v25, 52
	s_waitcnt vmcnt(12)
	v_pk_fma_f32 v[16:17], v[142:143], s[22:23], v[16:17] op_sel_hi:[0,1,1]
	v_pk_fma_f32 v[14:15], v[142:143], s[24:25], v[14:15] op_sel_hi:[0,1,1]
	v_pk_fma_f32 v[12:13], v[142:143], s[26:27], v[12:13] op_sel_hi:[0,1,1]
	v_pk_fma_f32 v[10:11], v[142:143], s[30:31], v[10:11] op_sel_hi:[0,1,1]
	v_readlane_b32 s22, v3, 53
	v_readlane_b32 s23, v19, 53
	v_readlane_b32 s24, v20, 53
	v_readlane_b32 s25, v21, 53
	v_readlane_b32 s26, v22, 53
	v_readlane_b32 s27, v23, 53
	v_readlane_b32 s30, v24, 53
	v_readlane_b32 s31, v25, 53
	s_waitcnt vmcnt(11)
	v_pk_fma_f32 v[16:17], v[144:145], s[6:7], v[16:17] op_sel_hi:[0,1,1]
	v_pk_fma_f32 v[14:15], v[144:145], s[8:9], v[14:15] op_sel_hi:[0,1,1]
	v_pk_fma_f32 v[12:13], v[144:145], s[10:11], v[12:13] op_sel_hi:[0,1,1]
	v_pk_fma_f32 v[10:11], v[144:145], s[12:13], v[10:11] op_sel_hi:[0,1,1]
	v_readlane_b32 s6, v3, 54
	v_readlane_b32 s7, v19, 54
	v_readlane_b32 s8, v20, 54
	v_readlane_b32 s9, v21, 54
	v_readlane_b32 s10, v22, 54
	v_readlane_b32 s11, v23, 54
	v_readlane_b32 s12, v24, 54
	v_readlane_b32 s13, v25, 54
	s_waitcnt vmcnt(10)
	v_pk_fma_f32 v[16:17], v[146:147], s[22:23], v[16:17] op_sel_hi:[0,1,1]
	v_pk_fma_f32 v[14:15], v[146:147], s[24:25], v[14:15] op_sel_hi:[0,1,1]
	v_pk_fma_f32 v[12:13], v[146:147], s[26:27], v[12:13] op_sel_hi:[0,1,1]
	v_pk_fma_f32 v[10:11], v[146:147], s[30:31], v[10:11] op_sel_hi:[0,1,1]
	v_readlane_b32 s22, v3, 55
	v_readlane_b32 s23, v19, 55
	v_readlane_b32 s24, v20, 55
	v_readlane_b32 s25, v21, 55
	v_readlane_b32 s26, v22, 55
	v_readlane_b32 s27, v23, 55
	v_readlane_b32 s30, v24, 55
	v_readlane_b32 s31, v25, 55
	s_waitcnt vmcnt(9)
	v_pk_fma_f32 v[16:17], v[148:149], s[6:7], v[16:17] op_sel_hi:[0,1,1]
	v_pk_fma_f32 v[14:15], v[148:149], s[8:9], v[14:15] op_sel_hi:[0,1,1]
	v_pk_fma_f32 v[12:13], v[148:149], s[10:11], v[12:13] op_sel_hi:[0,1,1]
	v_pk_fma_f32 v[10:11], v[148:149], s[12:13], v[10:11] op_sel_hi:[0,1,1]
	v_readlane_b32 s6, v3, 56
	v_readlane_b32 s7, v19, 56
	v_readlane_b32 s8, v20, 56
	v_readlane_b32 s9, v21, 56
	v_readlane_b32 s10, v22, 56
	v_readlane_b32 s11, v23, 56
	v_readlane_b32 s12, v24, 56
	v_readlane_b32 s13, v25, 56
	s_waitcnt vmcnt(8)
	v_pk_fma_f32 v[16:17], v[150:151], s[22:23], v[16:17] op_sel_hi:[0,1,1]
	v_pk_fma_f32 v[14:15], v[150:151], s[24:25], v[14:15] op_sel_hi:[0,1,1]
	v_pk_fma_f32 v[12:13], v[150:151], s[26:27], v[12:13] op_sel_hi:[0,1,1]
	v_pk_fma_f32 v[10:11], v[150:151], s[30:31], v[10:11] op_sel_hi:[0,1,1]
	v_readlane_b32 s22, v3, 57
	v_readlane_b32 s23, v19, 57
	v_readlane_b32 s24, v20, 57
	v_readlane_b32 s25, v21, 57
	v_readlane_b32 s26, v22, 57
	v_readlane_b32 s27, v23, 57
	v_readlane_b32 s30, v24, 57
	v_readlane_b32 s31, v25, 57
	s_waitcnt vmcnt(7)
	v_pk_fma_f32 v[16:17], v[152:153], s[6:7], v[16:17] op_sel_hi:[0,1,1]
	v_pk_fma_f32 v[14:15], v[152:153], s[8:9], v[14:15] op_sel_hi:[0,1,1]
	v_pk_fma_f32 v[12:13], v[152:153], s[10:11], v[12:13] op_sel_hi:[0,1,1]
	v_pk_fma_f32 v[10:11], v[152:153], s[12:13], v[10:11] op_sel_hi:[0,1,1]
	v_readlane_b32 s6, v3, 58
	v_readlane_b32 s7, v19, 58
	v_readlane_b32 s8, v20, 58
	v_readlane_b32 s9, v21, 58
	v_readlane_b32 s10, v22, 58
	v_readlane_b32 s11, v23, 58
	v_readlane_b32 s12, v24, 58
	v_readlane_b32 s13, v25, 58
	s_waitcnt vmcnt(6)
	v_pk_fma_f32 v[16:17], v[154:155], s[22:23], v[16:17] op_sel_hi:[0,1,1]
	v_pk_fma_f32 v[14:15], v[154:155], s[24:25], v[14:15] op_sel_hi:[0,1,1]
	v_pk_fma_f32 v[12:13], v[154:155], s[26:27], v[12:13] op_sel_hi:[0,1,1]
	v_pk_fma_f32 v[10:11], v[154:155], s[30:31], v[10:11] op_sel_hi:[0,1,1]
	v_readlane_b32 s22, v3, 59
	v_readlane_b32 s23, v19, 59
	v_readlane_b32 s24, v20, 59
	v_readlane_b32 s25, v21, 59
	v_readlane_b32 s26, v22, 59
	v_readlane_b32 s27, v23, 59
	v_readlane_b32 s30, v24, 59
	v_readlane_b32 s31, v25, 59
	s_waitcnt vmcnt(5)
	v_pk_fma_f32 v[16:17], v[156:157], s[6:7], v[16:17] op_sel_hi:[0,1,1]
	v_pk_fma_f32 v[14:15], v[156:157], s[8:9], v[14:15] op_sel_hi:[0,1,1]
	v_pk_fma_f32 v[12:13], v[156:157], s[10:11], v[12:13] op_sel_hi:[0,1,1]
	v_pk_fma_f32 v[10:11], v[156:157], s[12:13], v[10:11] op_sel_hi:[0,1,1]
	v_readlane_b32 s6, v3, 60
	v_readlane_b32 s7, v19, 60
	v_readlane_b32 s8, v20, 60
	v_readlane_b32 s9, v21, 60
	v_readlane_b32 s10, v22, 60
	v_readlane_b32 s11, v23, 60
	v_readlane_b32 s12, v24, 60
	v_readlane_b32 s13, v25, 60
	s_waitcnt vmcnt(4)
	v_pk_fma_f32 v[16:17], v[158:159], s[22:23], v[16:17] op_sel_hi:[0,1,1]
	v_pk_fma_f32 v[14:15], v[158:159], s[24:25], v[14:15] op_sel_hi:[0,1,1]
	v_pk_fma_f32 v[12:13], v[158:159], s[26:27], v[12:13] op_sel_hi:[0,1,1]
	v_pk_fma_f32 v[10:11], v[158:159], s[30:31], v[10:11] op_sel_hi:[0,1,1]
	v_readlane_b32 s22, v3, 61
	v_readlane_b32 s23, v19, 61
	v_readlane_b32 s24, v20, 61
	v_readlane_b32 s25, v21, 61
	v_readlane_b32 s26, v22, 61
	v_readlane_b32 s27, v23, 61
	v_readlane_b32 s30, v24, 61
	v_readlane_b32 s31, v25, 61
	s_waitcnt vmcnt(3)
	v_pk_fma_f32 v[16:17], v[164:165], s[6:7], v[16:17] op_sel_hi:[0,1,1]
	v_pk_fma_f32 v[14:15], v[164:165], s[8:9], v[14:15] op_sel_hi:[0,1,1]
	v_pk_fma_f32 v[12:13], v[164:165], s[10:11], v[12:13] op_sel_hi:[0,1,1]
	v_pk_fma_f32 v[10:11], v[164:165], s[12:13], v[10:11] op_sel_hi:[0,1,1]
	v_readlane_b32 s6, v3, 62
	v_readlane_b32 s7, v19, 62
	v_readlane_b32 s8, v20, 62
	v_readlane_b32 s9, v21, 62
	v_readlane_b32 s10, v22, 62
	v_readlane_b32 s11, v23, 62
	v_readlane_b32 s12, v24, 62
	v_readlane_b32 s13, v25, 62
	s_waitcnt vmcnt(2)
	v_pk_fma_f32 v[16:17], v[166:167], s[22:23], v[16:17] op_sel_hi:[0,1,1]
	v_pk_fma_f32 v[14:15], v[166:167], s[24:25], v[14:15] op_sel_hi:[0,1,1]
	v_pk_fma_f32 v[12:13], v[166:167], s[26:27], v[12:13] op_sel_hi:[0,1,1]
	v_pk_fma_f32 v[10:11], v[166:167], s[30:31], v[10:11] op_sel_hi:[0,1,1]
	v_readlane_b32 s22, v3, 63
	v_readlane_b32 s23, v19, 63
	v_readlane_b32 s24, v20, 63
	v_readlane_b32 s25, v21, 63
	v_readlane_b32 s26, v22, 63
	v_readlane_b32 s27, v23, 63
	v_readlane_b32 s30, v24, 63
	v_readlane_b32 s31, v25, 63
	s_waitcnt vmcnt(1)
	v_pk_fma_f32 v[16:17], v[168:169], s[6:7], v[16:17] op_sel_hi:[0,1,1]
	v_pk_fma_f32 v[14:15], v[168:169], s[8:9], v[14:15] op_sel_hi:[0,1,1]
	v_pk_fma_f32 v[12:13], v[168:169], s[10:11], v[12:13] op_sel_hi:[0,1,1]
	v_pk_fma_f32 v[10:11], v[168:169], s[12:13], v[10:11] op_sel_hi:[0,1,1]
	s_waitcnt vmcnt(0)
	v_pk_fma_f32 v[16:17], v[170:171], s[22:23], v[16:17] op_sel_hi:[0,1,1]
	v_pk_fma_f32 v[14:15], v[170:171], s[24:25], v[14:15] op_sel_hi:[0,1,1]
	v_pk_fma_f32 v[12:13], v[170:171], s[26:27], v[12:13] op_sel_hi:[0,1,1]
	v_pk_fma_f32 v[10:11], v[170:171], s[30:31], v[10:11] op_sel_hi:[0,1,1]
	v_lshl_add_u64 v[8:9], v[8:9], 0, s[14:15]
	global_load_dword v40, v[8:9], off
	v_lshl_add_u64 v[8:9], v[8:9], 0, s[14:15]
	global_load_dword v42, v[8:9], off
	v_lshl_add_u64 v[8:9], v[8:9], 0, s[14:15]
	global_load_dword v44, v[8:9], off
	v_lshl_add_u64 v[8:9], v[8:9], 0, s[14:15]
	global_load_dword v46, v[8:9], off
	v_lshl_add_u64 v[8:9], v[8:9], 0, s[14:15]
	global_load_dword v48, v[8:9], off
	v_lshl_add_u64 v[8:9], v[8:9], 0, s[14:15]
	global_load_dword v50, v[8:9], off
	v_lshl_add_u64 v[8:9], v[8:9], 0, s[14:15]
	global_load_dword v52, v[8:9], off
	v_lshl_add_u64 v[8:9], v[8:9], 0, s[14:15]
	global_load_dword v54, v[8:9], off
	v_lshl_add_u64 v[8:9], v[8:9], 0, s[14:15]
	global_load_dword v56, v[8:9], off
	v_lshl_add_u64 v[8:9], v[8:9], 0, s[14:15]
	global_load_dword v58, v[8:9], off
	v_lshl_add_u64 v[8:9], v[8:9], 0, s[14:15]
	global_load_dword v60, v[8:9], off
	v_lshl_add_u64 v[8:9], v[8:9], 0, s[14:15]
	global_load_dword v62, v[8:9], off
	v_lshl_add_u64 v[8:9], v[8:9], 0, s[14:15]
	global_load_dword v64, v[8:9], off
	v_lshl_add_u64 v[8:9], v[8:9], 0, s[14:15]
	global_load_dword v66, v[8:9], off
	v_lshl_add_u64 v[8:9], v[8:9], 0, s[14:15]
	global_load_dword v68, v[8:9], off
	v_lshl_add_u64 v[8:9], v[8:9], 0, s[14:15]
	global_load_dword v70, v[8:9], off
	v_lshl_add_u64 v[8:9], v[8:9], 0, s[14:15]
	global_load_dword v72, v[8:9], off
	v_lshl_add_u64 v[8:9], v[8:9], 0, s[14:15]
	global_load_dword v74, v[8:9], off
	v_lshl_add_u64 v[8:9], v[8:9], 0, s[14:15]
	global_load_dword v76, v[8:9], off
	v_lshl_add_u64 v[8:9], v[8:9], 0, s[14:15]
	global_load_dword v78, v[8:9], off
	v_lshl_add_u64 v[8:9], v[8:9], 0, s[14:15]
	global_load_dword v80, v[8:9], off
	v_lshl_add_u64 v[8:9], v[8:9], 0, s[14:15]
	global_load_dword v82, v[8:9], off
	v_lshl_add_u64 v[8:9], v[8:9], 0, s[14:15]
	global_load_dword v84, v[8:9], off
	v_lshl_add_u64 v[8:9], v[8:9], 0, s[14:15]
	global_load_dword v86, v[8:9], off
	v_lshl_add_u64 v[8:9], v[8:9], 0, s[14:15]
	global_load_dword v88, v[8:9], off
	v_lshl_add_u64 v[8:9], v[8:9], 0, s[14:15]
	global_load_dword v90, v[8:9], off
	v_lshl_add_u64 v[8:9], v[8:9], 0, s[14:15]
	global_load_dword v92, v[8:9], off
	v_lshl_add_u64 v[8:9], v[8:9], 0, s[14:15]
	global_load_dword v94, v[8:9], off
	v_lshl_add_u64 v[8:9], v[8:9], 0, s[14:15]
	global_load_dword v96, v[8:9], off
	v_lshl_add_u64 v[8:9], v[8:9], 0, s[14:15]
	global_load_dword v98, v[8:9], off
	v_lshl_add_u64 v[8:9], v[8:9], 0, s[14:15]
	global_load_dword v100, v[8:9], off
	v_lshl_add_u64 v[8:9], v[8:9], 0, s[14:15]
	global_load_dword v102, v[8:9], off
	v_lshl_add_u64 v[8:9], v[8:9], 0, s[14:15]
	global_load_dword v104, v[8:9], off
	v_lshl_add_u64 v[8:9], v[8:9], 0, s[14:15]
	global_load_dword v106, v[8:9], off
	v_lshl_add_u64 v[8:9], v[8:9], 0, s[14:15]
	global_load_dword v108, v[8:9], off
	v_lshl_add_u64 v[8:9], v[8:9], 0, s[14:15]
	global_load_dword v110, v[8:9], off
	v_lshl_add_u64 v[8:9], v[8:9], 0, s[14:15]
	global_load_dword v112, v[8:9], off
	v_lshl_add_u64 v[8:9], v[8:9], 0, s[14:15]
	global_load_dword v114, v[8:9], off
	v_lshl_add_u64 v[8:9], v[8:9], 0, s[14:15]
	global_load_dword v116, v[8:9], off
	v_lshl_add_u64 v[8:9], v[8:9], 0, s[14:15]
	global_load_dword v118, v[8:9], off
	v_lshl_add_u64 v[8:9], v[8:9], 0, s[14:15]
	global_load_dword v120, v[8:9], off
	v_lshl_add_u64 v[8:9], v[8:9], 0, s[14:15]
	global_load_dword v122, v[8:9], off
	v_lshl_add_u64 v[8:9], v[8:9], 0, s[14:15]
	global_load_dword v124, v[8:9], off
	v_lshl_add_u64 v[8:9], v[8:9], 0, s[14:15]
	global_load_dword v126, v[8:9], off
	v_lshl_add_u64 v[8:9], v[8:9], 0, s[14:15]
	global_load_dword v128, v[8:9], off
	v_lshl_add_u64 v[8:9], v[8:9], 0, s[14:15]
	global_load_dword v130, v[8:9], off
	v_lshl_add_u64 v[8:9], v[8:9], 0, s[14:15]
	global_load_dword v132, v[8:9], off
	v_lshl_add_u64 v[8:9], v[8:9], 0, s[14:15]
	global_load_dword v134, v[8:9], off
	v_lshl_add_u64 v[8:9], v[8:9], 0, s[14:15]
	global_load_dword v136, v[8:9], off
	v_lshl_add_u64 v[8:9], v[8:9], 0, s[14:15]
	global_load_dword v138, v[8:9], off
	v_lshl_add_u64 v[8:9], v[8:9], 0, s[14:15]
	global_load_dword v140, v[8:9], off
	v_lshl_add_u64 v[8:9], v[8:9], 0, s[14:15]
	global_load_dword v142, v[8:9], off
	v_lshl_add_u64 v[8:9], v[8:9], 0, s[14:15]
	global_load_dword v144, v[8:9], off
	v_lshl_add_u64 v[8:9], v[8:9], 0, s[14:15]
	global_load_dword v146, v[8:9], off
	v_lshl_add_u64 v[8:9], v[8:9], 0, s[14:15]
	global_load_dword v148, v[8:9], off
	v_lshl_add_u64 v[8:9], v[8:9], 0, s[14:15]
	global_load_dword v150, v[8:9], off
	v_lshl_add_u64 v[8:9], v[8:9], 0, s[14:15]
	global_load_dword v152, v[8:9], off
	v_lshl_add_u64 v[8:9], v[8:9], 0, s[14:15]
	global_load_dword v154, v[8:9], off
	v_lshl_add_u64 v[8:9], v[8:9], 0, s[14:15]
	global_load_dword v156, v[8:9], off
	v_lshl_add_u64 v[8:9], v[8:9], 0, s[14:15]
	global_load_dword v158, v[8:9], off
	v_lshl_add_u64 v[8:9], v[8:9], 0, s[14:15]
	global_load_dword v164, v[8:9], off
	v_lshl_add_u64 v[8:9], v[8:9], 0, s[14:15]
	global_load_dword v166, v[8:9], off
	v_lshl_add_u64 v[8:9], v[8:9], 0, s[14:15]
	global_load_dword v168, v[8:9], off
	v_lshl_add_u64 v[8:9], v[8:9], 0, s[14:15]
	global_load_dword v170, v[8:9], off
	s_waitcnt vmcnt(63)
	v_readlane_b32 s6, v26, 0
	v_readlane_b32 s7, v27, 0
	v_readlane_b32 s8, v28, 0
	v_readlane_b32 s9, v29, 0
	v_readlane_b32 s10, v30, 0
	v_readlane_b32 s11, v31, 0
	v_readlane_b32 s12, v32, 0
	v_readlane_b32 s13, v33, 0
	v_readlane_b32 s22, v26, 1
	v_readlane_b32 s23, v27, 1
	v_readlane_b32 s24, v28, 1
	v_readlane_b32 s25, v29, 1
	v_readlane_b32 s26, v30, 1
	v_readlane_b32 s27, v31, 1
	v_readlane_b32 s30, v32, 1
	v_readlane_b32 s31, v33, 1
	v_pk_fma_f32 v[16:17], v[40:41], s[6:7], v[16:17] op_sel_hi:[0,1,1]
	v_pk_fma_f32 v[14:15], v[40:41], s[8:9], v[14:15] op_sel_hi:[0,1,1]
	v_pk_fma_f32 v[12:13], v[40:41], s[10:11], v[12:13] op_sel_hi:[0,1,1]
	v_pk_fma_f32 v[10:11], v[40:41], s[12:13], v[10:11] op_sel_hi:[0,1,1]
	v_readlane_b32 s6, v26, 2
	v_readlane_b32 s7, v27, 2
	v_readlane_b32 s8, v28, 2
	v_readlane_b32 s9, v29, 2
	v_readlane_b32 s10, v30, 2
	v_readlane_b32 s11, v31, 2
	v_readlane_b32 s12, v32, 2
	v_readlane_b32 s13, v33, 2
	s_waitcnt vmcnt(62)
	v_pk_fma_f32 v[16:17], v[42:43], s[22:23], v[16:17] op_sel_hi:[0,1,1]
	v_pk_fma_f32 v[14:15], v[42:43], s[24:25], v[14:15] op_sel_hi:[0,1,1]
	v_pk_fma_f32 v[12:13], v[42:43], s[26:27], v[12:13] op_sel_hi:[0,1,1]
	v_pk_fma_f32 v[10:11], v[42:43], s[30:31], v[10:11] op_sel_hi:[0,1,1]
	v_readlane_b32 s22, v26, 3
	v_readlane_b32 s23, v27, 3
	v_readlane_b32 s24, v28, 3
	v_readlane_b32 s25, v29, 3
	v_readlane_b32 s26, v30, 3
	v_readlane_b32 s27, v31, 3
	v_readlane_b32 s30, v32, 3
	v_readlane_b32 s31, v33, 3
	s_waitcnt vmcnt(61)
	v_pk_fma_f32 v[16:17], v[44:45], s[6:7], v[16:17] op_sel_hi:[0,1,1]
	v_pk_fma_f32 v[14:15], v[44:45], s[8:9], v[14:15] op_sel_hi:[0,1,1]
	v_pk_fma_f32 v[12:13], v[44:45], s[10:11], v[12:13] op_sel_hi:[0,1,1]
	v_pk_fma_f32 v[10:11], v[44:45], s[12:13], v[10:11] op_sel_hi:[0,1,1]
	v_readlane_b32 s6, v26, 4
	v_readlane_b32 s7, v27, 4
	v_readlane_b32 s8, v28, 4
	v_readlane_b32 s9, v29, 4
	v_readlane_b32 s10, v30, 4
	v_readlane_b32 s11, v31, 4
	v_readlane_b32 s12, v32, 4
	v_readlane_b32 s13, v33, 4
	s_waitcnt vmcnt(60)
	v_pk_fma_f32 v[16:17], v[46:47], s[22:23], v[16:17] op_sel_hi:[0,1,1]
	v_pk_fma_f32 v[14:15], v[46:47], s[24:25], v[14:15] op_sel_hi:[0,1,1]
	v_pk_fma_f32 v[12:13], v[46:47], s[26:27], v[12:13] op_sel_hi:[0,1,1]
	v_pk_fma_f32 v[10:11], v[46:47], s[30:31], v[10:11] op_sel_hi:[0,1,1]
	v_readlane_b32 s22, v26, 5
	v_readlane_b32 s23, v27, 5
	v_readlane_b32 s24, v28, 5
	v_readlane_b32 s25, v29, 5
	v_readlane_b32 s26, v30, 5
	v_readlane_b32 s27, v31, 5
	v_readlane_b32 s30, v32, 5
	v_readlane_b32 s31, v33, 5
	s_waitcnt vmcnt(59)
	v_pk_fma_f32 v[16:17], v[48:49], s[6:7], v[16:17] op_sel_hi:[0,1,1]
	v_pk_fma_f32 v[14:15], v[48:49], s[8:9], v[14:15] op_sel_hi:[0,1,1]
	v_pk_fma_f32 v[12:13], v[48:49], s[10:11], v[12:13] op_sel_hi:[0,1,1]
	v_pk_fma_f32 v[10:11], v[48:49], s[12:13], v[10:11] op_sel_hi:[0,1,1]
	v_readlane_b32 s6, v26, 6
	v_readlane_b32 s7, v27, 6
	v_readlane_b32 s8, v28, 6
	v_readlane_b32 s9, v29, 6
	v_readlane_b32 s10, v30, 6
	v_readlane_b32 s11, v31, 6
	v_readlane_b32 s12, v32, 6
	v_readlane_b32 s13, v33, 6
	s_waitcnt vmcnt(58)
	v_pk_fma_f32 v[16:17], v[50:51], s[22:23], v[16:17] op_sel_hi:[0,1,1]
	v_pk_fma_f32 v[14:15], v[50:51], s[24:25], v[14:15] op_sel_hi:[0,1,1]
	v_pk_fma_f32 v[12:13], v[50:51], s[26:27], v[12:13] op_sel_hi:[0,1,1]
	v_pk_fma_f32 v[10:11], v[50:51], s[30:31], v[10:11] op_sel_hi:[0,1,1]
	v_readlane_b32 s22, v26, 7
	v_readlane_b32 s23, v27, 7
	v_readlane_b32 s24, v28, 7
	v_readlane_b32 s25, v29, 7
	v_readlane_b32 s26, v30, 7
	v_readlane_b32 s27, v31, 7
	v_readlane_b32 s30, v32, 7
	v_readlane_b32 s31, v33, 7
	s_waitcnt vmcnt(57)
	v_pk_fma_f32 v[16:17], v[52:53], s[6:7], v[16:17] op_sel_hi:[0,1,1]
	v_pk_fma_f32 v[14:15], v[52:53], s[8:9], v[14:15] op_sel_hi:[0,1,1]
	v_pk_fma_f32 v[12:13], v[52:53], s[10:11], v[12:13] op_sel_hi:[0,1,1]
	v_pk_fma_f32 v[10:11], v[52:53], s[12:13], v[10:11] op_sel_hi:[0,1,1]
	v_readlane_b32 s6, v26, 8
	v_readlane_b32 s7, v27, 8
	v_readlane_b32 s8, v28, 8
	v_readlane_b32 s9, v29, 8
	v_readlane_b32 s10, v30, 8
	v_readlane_b32 s11, v31, 8
	v_readlane_b32 s12, v32, 8
	v_readlane_b32 s13, v33, 8
	s_waitcnt vmcnt(56)
	v_pk_fma_f32 v[16:17], v[54:55], s[22:23], v[16:17] op_sel_hi:[0,1,1]
	v_pk_fma_f32 v[14:15], v[54:55], s[24:25], v[14:15] op_sel_hi:[0,1,1]
	v_pk_fma_f32 v[12:13], v[54:55], s[26:27], v[12:13] op_sel_hi:[0,1,1]
	v_pk_fma_f32 v[10:11], v[54:55], s[30:31], v[10:11] op_sel_hi:[0,1,1]
	v_readlane_b32 s22, v26, 9
	v_readlane_b32 s23, v27, 9
	v_readlane_b32 s24, v28, 9
	v_readlane_b32 s25, v29, 9
	v_readlane_b32 s26, v30, 9
	v_readlane_b32 s27, v31, 9
	v_readlane_b32 s30, v32, 9
	v_readlane_b32 s31, v33, 9
	s_waitcnt vmcnt(55)
	v_pk_fma_f32 v[16:17], v[56:57], s[6:7], v[16:17] op_sel_hi:[0,1,1]
	v_pk_fma_f32 v[14:15], v[56:57], s[8:9], v[14:15] op_sel_hi:[0,1,1]
	v_pk_fma_f32 v[12:13], v[56:57], s[10:11], v[12:13] op_sel_hi:[0,1,1]
	v_pk_fma_f32 v[10:11], v[56:57], s[12:13], v[10:11] op_sel_hi:[0,1,1]
	v_readlane_b32 s6, v26, 10
	v_readlane_b32 s7, v27, 10
	v_readlane_b32 s8, v28, 10
	v_readlane_b32 s9, v29, 10
	v_readlane_b32 s10, v30, 10
	v_readlane_b32 s11, v31, 10
	v_readlane_b32 s12, v32, 10
	v_readlane_b32 s13, v33, 10
	s_waitcnt vmcnt(54)
	v_pk_fma_f32 v[16:17], v[58:59], s[22:23], v[16:17] op_sel_hi:[0,1,1]
	v_pk_fma_f32 v[14:15], v[58:59], s[24:25], v[14:15] op_sel_hi:[0,1,1]
	v_pk_fma_f32 v[12:13], v[58:59], s[26:27], v[12:13] op_sel_hi:[0,1,1]
	v_pk_fma_f32 v[10:11], v[58:59], s[30:31], v[10:11] op_sel_hi:[0,1,1]
	v_readlane_b32 s22, v26, 11
	v_readlane_b32 s23, v27, 11
	v_readlane_b32 s24, v28, 11
	v_readlane_b32 s25, v29, 11
	v_readlane_b32 s26, v30, 11
	v_readlane_b32 s27, v31, 11
	v_readlane_b32 s30, v32, 11
	v_readlane_b32 s31, v33, 11
	s_waitcnt vmcnt(53)
	v_pk_fma_f32 v[16:17], v[60:61], s[6:7], v[16:17] op_sel_hi:[0,1,1]
	v_pk_fma_f32 v[14:15], v[60:61], s[8:9], v[14:15] op_sel_hi:[0,1,1]
	v_pk_fma_f32 v[12:13], v[60:61], s[10:11], v[12:13] op_sel_hi:[0,1,1]
	v_pk_fma_f32 v[10:11], v[60:61], s[12:13], v[10:11] op_sel_hi:[0,1,1]
	v_readlane_b32 s6, v26, 12
	v_readlane_b32 s7, v27, 12
	v_readlane_b32 s8, v28, 12
	v_readlane_b32 s9, v29, 12
	v_readlane_b32 s10, v30, 12
	v_readlane_b32 s11, v31, 12
	v_readlane_b32 s12, v32, 12
	v_readlane_b32 s13, v33, 12
	s_waitcnt vmcnt(52)
	v_pk_fma_f32 v[16:17], v[62:63], s[22:23], v[16:17] op_sel_hi:[0,1,1]
	v_pk_fma_f32 v[14:15], v[62:63], s[24:25], v[14:15] op_sel_hi:[0,1,1]
	v_pk_fma_f32 v[12:13], v[62:63], s[26:27], v[12:13] op_sel_hi:[0,1,1]
	v_pk_fma_f32 v[10:11], v[62:63], s[30:31], v[10:11] op_sel_hi:[0,1,1]
	v_readlane_b32 s22, v26, 13
	v_readlane_b32 s23, v27, 13
	v_readlane_b32 s24, v28, 13
	v_readlane_b32 s25, v29, 13
	v_readlane_b32 s26, v30, 13
	v_readlane_b32 s27, v31, 13
	v_readlane_b32 s30, v32, 13
	v_readlane_b32 s31, v33, 13
	s_waitcnt vmcnt(51)
	v_pk_fma_f32 v[16:17], v[64:65], s[6:7], v[16:17] op_sel_hi:[0,1,1]
	v_pk_fma_f32 v[14:15], v[64:65], s[8:9], v[14:15] op_sel_hi:[0,1,1]
	v_pk_fma_f32 v[12:13], v[64:65], s[10:11], v[12:13] op_sel_hi:[0,1,1]
	v_pk_fma_f32 v[10:11], v[64:65], s[12:13], v[10:11] op_sel_hi:[0,1,1]
	v_readlane_b32 s6, v26, 14
	v_readlane_b32 s7, v27, 14
	v_readlane_b32 s8, v28, 14
	v_readlane_b32 s9, v29, 14
	v_readlane_b32 s10, v30, 14
	v_readlane_b32 s11, v31, 14
	v_readlane_b32 s12, v32, 14
	v_readlane_b32 s13, v33, 14
	s_waitcnt vmcnt(50)
	v_pk_fma_f32 v[16:17], v[66:67], s[22:23], v[16:17] op_sel_hi:[0,1,1]
	v_pk_fma_f32 v[14:15], v[66:67], s[24:25], v[14:15] op_sel_hi:[0,1,1]
	v_pk_fma_f32 v[12:13], v[66:67], s[26:27], v[12:13] op_sel_hi:[0,1,1]
	v_pk_fma_f32 v[10:11], v[66:67], s[30:31], v[10:11] op_sel_hi:[0,1,1]
	v_readlane_b32 s22, v26, 15
	v_readlane_b32 s23, v27, 15
	v_readlane_b32 s24, v28, 15
	v_readlane_b32 s25, v29, 15
	v_readlane_b32 s26, v30, 15
	v_readlane_b32 s27, v31, 15
	v_readlane_b32 s30, v32, 15
	v_readlane_b32 s31, v33, 15
	s_waitcnt vmcnt(49)
	v_pk_fma_f32 v[16:17], v[68:69], s[6:7], v[16:17] op_sel_hi:[0,1,1]
	v_pk_fma_f32 v[14:15], v[68:69], s[8:9], v[14:15] op_sel_hi:[0,1,1]
	v_pk_fma_f32 v[12:13], v[68:69], s[10:11], v[12:13] op_sel_hi:[0,1,1]
	v_pk_fma_f32 v[10:11], v[68:69], s[12:13], v[10:11] op_sel_hi:[0,1,1]
	v_readlane_b32 s6, v26, 16
	v_readlane_b32 s7, v27, 16
	v_readlane_b32 s8, v28, 16
	v_readlane_b32 s9, v29, 16
	v_readlane_b32 s10, v30, 16
	v_readlane_b32 s11, v31, 16
	v_readlane_b32 s12, v32, 16
	v_readlane_b32 s13, v33, 16
	s_waitcnt vmcnt(48)
	v_pk_fma_f32 v[16:17], v[70:71], s[22:23], v[16:17] op_sel_hi:[0,1,1]
	v_pk_fma_f32 v[14:15], v[70:71], s[24:25], v[14:15] op_sel_hi:[0,1,1]
	v_pk_fma_f32 v[12:13], v[70:71], s[26:27], v[12:13] op_sel_hi:[0,1,1]
	v_pk_fma_f32 v[10:11], v[70:71], s[30:31], v[10:11] op_sel_hi:[0,1,1]
	v_readlane_b32 s22, v26, 17
	v_readlane_b32 s23, v27, 17
	v_readlane_b32 s24, v28, 17
	v_readlane_b32 s25, v29, 17
	v_readlane_b32 s26, v30, 17
	v_readlane_b32 s27, v31, 17
	v_readlane_b32 s30, v32, 17
	v_readlane_b32 s31, v33, 17
	s_waitcnt vmcnt(47)
	v_pk_fma_f32 v[16:17], v[72:73], s[6:7], v[16:17] op_sel_hi:[0,1,1]
	v_pk_fma_f32 v[14:15], v[72:73], s[8:9], v[14:15] op_sel_hi:[0,1,1]
	v_pk_fma_f32 v[12:13], v[72:73], s[10:11], v[12:13] op_sel_hi:[0,1,1]
	v_pk_fma_f32 v[10:11], v[72:73], s[12:13], v[10:11] op_sel_hi:[0,1,1]
	v_readlane_b32 s6, v26, 18
	v_readlane_b32 s7, v27, 18
	v_readlane_b32 s8, v28, 18
	v_readlane_b32 s9, v29, 18
	v_readlane_b32 s10, v30, 18
	v_readlane_b32 s11, v31, 18
	v_readlane_b32 s12, v32, 18
	v_readlane_b32 s13, v33, 18
	s_waitcnt vmcnt(46)
	v_pk_fma_f32 v[16:17], v[74:75], s[22:23], v[16:17] op_sel_hi:[0,1,1]
	v_pk_fma_f32 v[14:15], v[74:75], s[24:25], v[14:15] op_sel_hi:[0,1,1]
	v_pk_fma_f32 v[12:13], v[74:75], s[26:27], v[12:13] op_sel_hi:[0,1,1]
	v_pk_fma_f32 v[10:11], v[74:75], s[30:31], v[10:11] op_sel_hi:[0,1,1]
	v_readlane_b32 s22, v26, 19
	v_readlane_b32 s23, v27, 19
	v_readlane_b32 s24, v28, 19
	v_readlane_b32 s25, v29, 19
	v_readlane_b32 s26, v30, 19
	v_readlane_b32 s27, v31, 19
	v_readlane_b32 s30, v32, 19
	v_readlane_b32 s31, v33, 19
	s_waitcnt vmcnt(45)
	v_pk_fma_f32 v[16:17], v[76:77], s[6:7], v[16:17] op_sel_hi:[0,1,1]
	v_pk_fma_f32 v[14:15], v[76:77], s[8:9], v[14:15] op_sel_hi:[0,1,1]
	v_pk_fma_f32 v[12:13], v[76:77], s[10:11], v[12:13] op_sel_hi:[0,1,1]
	v_pk_fma_f32 v[10:11], v[76:77], s[12:13], v[10:11] op_sel_hi:[0,1,1]
	v_readlane_b32 s6, v26, 20
	v_readlane_b32 s7, v27, 20
	v_readlane_b32 s8, v28, 20
	v_readlane_b32 s9, v29, 20
	v_readlane_b32 s10, v30, 20
	v_readlane_b32 s11, v31, 20
	v_readlane_b32 s12, v32, 20
	v_readlane_b32 s13, v33, 20
	s_waitcnt vmcnt(44)
	v_pk_fma_f32 v[16:17], v[78:79], s[22:23], v[16:17] op_sel_hi:[0,1,1]
	v_pk_fma_f32 v[14:15], v[78:79], s[24:25], v[14:15] op_sel_hi:[0,1,1]
	v_pk_fma_f32 v[12:13], v[78:79], s[26:27], v[12:13] op_sel_hi:[0,1,1]
	v_pk_fma_f32 v[10:11], v[78:79], s[30:31], v[10:11] op_sel_hi:[0,1,1]
	v_readlane_b32 s22, v26, 21
	v_readlane_b32 s23, v27, 21
	v_readlane_b32 s24, v28, 21
	v_readlane_b32 s25, v29, 21
	v_readlane_b32 s26, v30, 21
	v_readlane_b32 s27, v31, 21
	v_readlane_b32 s30, v32, 21
	v_readlane_b32 s31, v33, 21
	s_waitcnt vmcnt(43)
	v_pk_fma_f32 v[16:17], v[80:81], s[6:7], v[16:17] op_sel_hi:[0,1,1]
	v_pk_fma_f32 v[14:15], v[80:81], s[8:9], v[14:15] op_sel_hi:[0,1,1]
	v_pk_fma_f32 v[12:13], v[80:81], s[10:11], v[12:13] op_sel_hi:[0,1,1]
	v_pk_fma_f32 v[10:11], v[80:81], s[12:13], v[10:11] op_sel_hi:[0,1,1]
	v_readlane_b32 s6, v26, 22
	v_readlane_b32 s7, v27, 22
	v_readlane_b32 s8, v28, 22
	v_readlane_b32 s9, v29, 22
	v_readlane_b32 s10, v30, 22
	v_readlane_b32 s11, v31, 22
	v_readlane_b32 s12, v32, 22
	v_readlane_b32 s13, v33, 22
	s_waitcnt vmcnt(42)
	v_pk_fma_f32 v[16:17], v[82:83], s[22:23], v[16:17] op_sel_hi:[0,1,1]
	v_pk_fma_f32 v[14:15], v[82:83], s[24:25], v[14:15] op_sel_hi:[0,1,1]
	v_pk_fma_f32 v[12:13], v[82:83], s[26:27], v[12:13] op_sel_hi:[0,1,1]
	v_pk_fma_f32 v[10:11], v[82:83], s[30:31], v[10:11] op_sel_hi:[0,1,1]
	v_readlane_b32 s22, v26, 23
	v_readlane_b32 s23, v27, 23
	v_readlane_b32 s24, v28, 23
	v_readlane_b32 s25, v29, 23
	v_readlane_b32 s26, v30, 23
	v_readlane_b32 s27, v31, 23
	v_readlane_b32 s30, v32, 23
	v_readlane_b32 s31, v33, 23
	s_waitcnt vmcnt(41)
	v_pk_fma_f32 v[16:17], v[84:85], s[6:7], v[16:17] op_sel_hi:[0,1,1]
	v_pk_fma_f32 v[14:15], v[84:85], s[8:9], v[14:15] op_sel_hi:[0,1,1]
	v_pk_fma_f32 v[12:13], v[84:85], s[10:11], v[12:13] op_sel_hi:[0,1,1]
	v_pk_fma_f32 v[10:11], v[84:85], s[12:13], v[10:11] op_sel_hi:[0,1,1]
	v_readlane_b32 s6, v26, 24
	v_readlane_b32 s7, v27, 24
	v_readlane_b32 s8, v28, 24
	v_readlane_b32 s9, v29, 24
	v_readlane_b32 s10, v30, 24
	v_readlane_b32 s11, v31, 24
	v_readlane_b32 s12, v32, 24
	v_readlane_b32 s13, v33, 24
	s_waitcnt vmcnt(40)
	v_pk_fma_f32 v[16:17], v[86:87], s[22:23], v[16:17] op_sel_hi:[0,1,1]
	v_pk_fma_f32 v[14:15], v[86:87], s[24:25], v[14:15] op_sel_hi:[0,1,1]
	v_pk_fma_f32 v[12:13], v[86:87], s[26:27], v[12:13] op_sel_hi:[0,1,1]
	v_pk_fma_f32 v[10:11], v[86:87], s[30:31], v[10:11] op_sel_hi:[0,1,1]
	v_readlane_b32 s22, v26, 25
	v_readlane_b32 s23, v27, 25
	v_readlane_b32 s24, v28, 25
	v_readlane_b32 s25, v29, 25
	v_readlane_b32 s26, v30, 25
	v_readlane_b32 s27, v31, 25
	v_readlane_b32 s30, v32, 25
	v_readlane_b32 s31, v33, 25
	s_waitcnt vmcnt(39)
	v_pk_fma_f32 v[16:17], v[88:89], s[6:7], v[16:17] op_sel_hi:[0,1,1]
	v_pk_fma_f32 v[14:15], v[88:89], s[8:9], v[14:15] op_sel_hi:[0,1,1]
	v_pk_fma_f32 v[12:13], v[88:89], s[10:11], v[12:13] op_sel_hi:[0,1,1]
	v_pk_fma_f32 v[10:11], v[88:89], s[12:13], v[10:11] op_sel_hi:[0,1,1]
	v_readlane_b32 s6, v26, 26
	v_readlane_b32 s7, v27, 26
	v_readlane_b32 s8, v28, 26
	v_readlane_b32 s9, v29, 26
	v_readlane_b32 s10, v30, 26
	v_readlane_b32 s11, v31, 26
	v_readlane_b32 s12, v32, 26
	v_readlane_b32 s13, v33, 26
	s_waitcnt vmcnt(38)
	v_pk_fma_f32 v[16:17], v[90:91], s[22:23], v[16:17] op_sel_hi:[0,1,1]
	v_pk_fma_f32 v[14:15], v[90:91], s[24:25], v[14:15] op_sel_hi:[0,1,1]
	v_pk_fma_f32 v[12:13], v[90:91], s[26:27], v[12:13] op_sel_hi:[0,1,1]
	v_pk_fma_f32 v[10:11], v[90:91], s[30:31], v[10:11] op_sel_hi:[0,1,1]
	v_readlane_b32 s22, v26, 27
	v_readlane_b32 s23, v27, 27
	v_readlane_b32 s24, v28, 27
	v_readlane_b32 s25, v29, 27
	v_readlane_b32 s26, v30, 27
	v_readlane_b32 s27, v31, 27
	v_readlane_b32 s30, v32, 27
	v_readlane_b32 s31, v33, 27
	s_waitcnt vmcnt(37)
	v_pk_fma_f32 v[16:17], v[92:93], s[6:7], v[16:17] op_sel_hi:[0,1,1]
	v_pk_fma_f32 v[14:15], v[92:93], s[8:9], v[14:15] op_sel_hi:[0,1,1]
	v_pk_fma_f32 v[12:13], v[92:93], s[10:11], v[12:13] op_sel_hi:[0,1,1]
	v_pk_fma_f32 v[10:11], v[92:93], s[12:13], v[10:11] op_sel_hi:[0,1,1]
	v_readlane_b32 s6, v26, 28
	v_readlane_b32 s7, v27, 28
	v_readlane_b32 s8, v28, 28
	v_readlane_b32 s9, v29, 28
	v_readlane_b32 s10, v30, 28
	v_readlane_b32 s11, v31, 28
	v_readlane_b32 s12, v32, 28
	v_readlane_b32 s13, v33, 28
	s_waitcnt vmcnt(36)
	v_pk_fma_f32 v[16:17], v[94:95], s[22:23], v[16:17] op_sel_hi:[0,1,1]
	v_pk_fma_f32 v[14:15], v[94:95], s[24:25], v[14:15] op_sel_hi:[0,1,1]
	v_pk_fma_f32 v[12:13], v[94:95], s[26:27], v[12:13] op_sel_hi:[0,1,1]
	v_pk_fma_f32 v[10:11], v[94:95], s[30:31], v[10:11] op_sel_hi:[0,1,1]
	v_readlane_b32 s22, v26, 29
	v_readlane_b32 s23, v27, 29
	v_readlane_b32 s24, v28, 29
	v_readlane_b32 s25, v29, 29
	v_readlane_b32 s26, v30, 29
	v_readlane_b32 s27, v31, 29
	v_readlane_b32 s30, v32, 29
	v_readlane_b32 s31, v33, 29
	s_waitcnt vmcnt(35)
	v_pk_fma_f32 v[16:17], v[96:97], s[6:7], v[16:17] op_sel_hi:[0,1,1]
	v_pk_fma_f32 v[14:15], v[96:97], s[8:9], v[14:15] op_sel_hi:[0,1,1]
	v_pk_fma_f32 v[12:13], v[96:97], s[10:11], v[12:13] op_sel_hi:[0,1,1]
	v_pk_fma_f32 v[10:11], v[96:97], s[12:13], v[10:11] op_sel_hi:[0,1,1]
	v_readlane_b32 s6, v26, 30
	v_readlane_b32 s7, v27, 30
	v_readlane_b32 s8, v28, 30
	v_readlane_b32 s9, v29, 30
	v_readlane_b32 s10, v30, 30
	v_readlane_b32 s11, v31, 30
	v_readlane_b32 s12, v32, 30
	v_readlane_b32 s13, v33, 30
	s_waitcnt vmcnt(34)
	v_pk_fma_f32 v[16:17], v[98:99], s[22:23], v[16:17] op_sel_hi:[0,1,1]
	v_pk_fma_f32 v[14:15], v[98:99], s[24:25], v[14:15] op_sel_hi:[0,1,1]
	v_pk_fma_f32 v[12:13], v[98:99], s[26:27], v[12:13] op_sel_hi:[0,1,1]
	v_pk_fma_f32 v[10:11], v[98:99], s[30:31], v[10:11] op_sel_hi:[0,1,1]
	v_readlane_b32 s22, v26, 31
	v_readlane_b32 s23, v27, 31
	v_readlane_b32 s24, v28, 31
	v_readlane_b32 s25, v29, 31
	v_readlane_b32 s26, v30, 31
	v_readlane_b32 s27, v31, 31
	v_readlane_b32 s30, v32, 31
	v_readlane_b32 s31, v33, 31
	s_waitcnt vmcnt(33)
	v_pk_fma_f32 v[16:17], v[100:101], s[6:7], v[16:17] op_sel_hi:[0,1,1]
	v_pk_fma_f32 v[14:15], v[100:101], s[8:9], v[14:15] op_sel_hi:[0,1,1]
	v_pk_fma_f32 v[12:13], v[100:101], s[10:11], v[12:13] op_sel_hi:[0,1,1]
	v_pk_fma_f32 v[10:11], v[100:101], s[12:13], v[10:11] op_sel_hi:[0,1,1]
	v_readlane_b32 s6, v26, 32
	v_readlane_b32 s7, v27, 32
	v_readlane_b32 s8, v28, 32
	v_readlane_b32 s9, v29, 32
	v_readlane_b32 s10, v30, 32
	v_readlane_b32 s11, v31, 32
	v_readlane_b32 s12, v32, 32
	v_readlane_b32 s13, v33, 32
	s_waitcnt vmcnt(32)
	v_pk_fma_f32 v[16:17], v[102:103], s[22:23], v[16:17] op_sel_hi:[0,1,1]
	v_pk_fma_f32 v[14:15], v[102:103], s[24:25], v[14:15] op_sel_hi:[0,1,1]
	v_pk_fma_f32 v[12:13], v[102:103], s[26:27], v[12:13] op_sel_hi:[0,1,1]
	v_pk_fma_f32 v[10:11], v[102:103], s[30:31], v[10:11] op_sel_hi:[0,1,1]
	v_readlane_b32 s22, v26, 33
	v_readlane_b32 s23, v27, 33
	v_readlane_b32 s24, v28, 33
	v_readlane_b32 s25, v29, 33
	v_readlane_b32 s26, v30, 33
	v_readlane_b32 s27, v31, 33
	v_readlane_b32 s30, v32, 33
	v_readlane_b32 s31, v33, 33
	s_waitcnt vmcnt(31)
	v_pk_fma_f32 v[16:17], v[104:105], s[6:7], v[16:17] op_sel_hi:[0,1,1]
	v_pk_fma_f32 v[14:15], v[104:105], s[8:9], v[14:15] op_sel_hi:[0,1,1]
	v_pk_fma_f32 v[12:13], v[104:105], s[10:11], v[12:13] op_sel_hi:[0,1,1]
	v_pk_fma_f32 v[10:11], v[104:105], s[12:13], v[10:11] op_sel_hi:[0,1,1]
	v_readlane_b32 s6, v26, 34
	v_readlane_b32 s7, v27, 34
	v_readlane_b32 s8, v28, 34
	v_readlane_b32 s9, v29, 34
	v_readlane_b32 s10, v30, 34
	v_readlane_b32 s11, v31, 34
	v_readlane_b32 s12, v32, 34
	v_readlane_b32 s13, v33, 34
	s_waitcnt vmcnt(30)
	v_pk_fma_f32 v[16:17], v[106:107], s[22:23], v[16:17] op_sel_hi:[0,1,1]
	v_pk_fma_f32 v[14:15], v[106:107], s[24:25], v[14:15] op_sel_hi:[0,1,1]
	v_pk_fma_f32 v[12:13], v[106:107], s[26:27], v[12:13] op_sel_hi:[0,1,1]
	v_pk_fma_f32 v[10:11], v[106:107], s[30:31], v[10:11] op_sel_hi:[0,1,1]
	v_readlane_b32 s22, v26, 35
	v_readlane_b32 s23, v27, 35
	v_readlane_b32 s24, v28, 35
	v_readlane_b32 s25, v29, 35
	v_readlane_b32 s26, v30, 35
	v_readlane_b32 s27, v31, 35
	v_readlane_b32 s30, v32, 35
	v_readlane_b32 s31, v33, 35
	s_waitcnt vmcnt(29)
	v_pk_fma_f32 v[16:17], v[108:109], s[6:7], v[16:17] op_sel_hi:[0,1,1]
	v_pk_fma_f32 v[14:15], v[108:109], s[8:9], v[14:15] op_sel_hi:[0,1,1]
	v_pk_fma_f32 v[12:13], v[108:109], s[10:11], v[12:13] op_sel_hi:[0,1,1]
	v_pk_fma_f32 v[10:11], v[108:109], s[12:13], v[10:11] op_sel_hi:[0,1,1]
	v_readlane_b32 s6, v26, 36
	v_readlane_b32 s7, v27, 36
	v_readlane_b32 s8, v28, 36
	v_readlane_b32 s9, v29, 36
	v_readlane_b32 s10, v30, 36
	v_readlane_b32 s11, v31, 36
	v_readlane_b32 s12, v32, 36
	v_readlane_b32 s13, v33, 36
	s_waitcnt vmcnt(28)
	v_pk_fma_f32 v[16:17], v[110:111], s[22:23], v[16:17] op_sel_hi:[0,1,1]
	v_pk_fma_f32 v[14:15], v[110:111], s[24:25], v[14:15] op_sel_hi:[0,1,1]
	v_pk_fma_f32 v[12:13], v[110:111], s[26:27], v[12:13] op_sel_hi:[0,1,1]
	v_pk_fma_f32 v[10:11], v[110:111], s[30:31], v[10:11] op_sel_hi:[0,1,1]
	v_readlane_b32 s22, v26, 37
	v_readlane_b32 s23, v27, 37
	v_readlane_b32 s24, v28, 37
	v_readlane_b32 s25, v29, 37
	v_readlane_b32 s26, v30, 37
	v_readlane_b32 s27, v31, 37
	v_readlane_b32 s30, v32, 37
	v_readlane_b32 s31, v33, 37
	s_waitcnt vmcnt(27)
	v_pk_fma_f32 v[16:17], v[112:113], s[6:7], v[16:17] op_sel_hi:[0,1,1]
	v_pk_fma_f32 v[14:15], v[112:113], s[8:9], v[14:15] op_sel_hi:[0,1,1]
	v_pk_fma_f32 v[12:13], v[112:113], s[10:11], v[12:13] op_sel_hi:[0,1,1]
	v_pk_fma_f32 v[10:11], v[112:113], s[12:13], v[10:11] op_sel_hi:[0,1,1]
	v_readlane_b32 s6, v26, 38
	v_readlane_b32 s7, v27, 38
	v_readlane_b32 s8, v28, 38
	v_readlane_b32 s9, v29, 38
	v_readlane_b32 s10, v30, 38
	v_readlane_b32 s11, v31, 38
	v_readlane_b32 s12, v32, 38
	v_readlane_b32 s13, v33, 38
	s_waitcnt vmcnt(26)
	v_pk_fma_f32 v[16:17], v[114:115], s[22:23], v[16:17] op_sel_hi:[0,1,1]
	v_pk_fma_f32 v[14:15], v[114:115], s[24:25], v[14:15] op_sel_hi:[0,1,1]
	v_pk_fma_f32 v[12:13], v[114:115], s[26:27], v[12:13] op_sel_hi:[0,1,1]
	v_pk_fma_f32 v[10:11], v[114:115], s[30:31], v[10:11] op_sel_hi:[0,1,1]
	v_readlane_b32 s22, v26, 39
	v_readlane_b32 s23, v27, 39
	v_readlane_b32 s24, v28, 39
	v_readlane_b32 s25, v29, 39
	v_readlane_b32 s26, v30, 39
	v_readlane_b32 s27, v31, 39
	v_readlane_b32 s30, v32, 39
	v_readlane_b32 s31, v33, 39
	s_waitcnt vmcnt(25)
	v_pk_fma_f32 v[16:17], v[116:117], s[6:7], v[16:17] op_sel_hi:[0,1,1]
	v_pk_fma_f32 v[14:15], v[116:117], s[8:9], v[14:15] op_sel_hi:[0,1,1]
	v_pk_fma_f32 v[12:13], v[116:117], s[10:11], v[12:13] op_sel_hi:[0,1,1]
	v_pk_fma_f32 v[10:11], v[116:117], s[12:13], v[10:11] op_sel_hi:[0,1,1]
	v_readlane_b32 s6, v26, 40
	v_readlane_b32 s7, v27, 40
	v_readlane_b32 s8, v28, 40
	v_readlane_b32 s9, v29, 40
	v_readlane_b32 s10, v30, 40
	v_readlane_b32 s11, v31, 40
	v_readlane_b32 s12, v32, 40
	v_readlane_b32 s13, v33, 40
	s_waitcnt vmcnt(24)
	v_pk_fma_f32 v[16:17], v[118:119], s[22:23], v[16:17] op_sel_hi:[0,1,1]
	v_pk_fma_f32 v[14:15], v[118:119], s[24:25], v[14:15] op_sel_hi:[0,1,1]
	v_pk_fma_f32 v[12:13], v[118:119], s[26:27], v[12:13] op_sel_hi:[0,1,1]
	v_pk_fma_f32 v[10:11], v[118:119], s[30:31], v[10:11] op_sel_hi:[0,1,1]
	v_readlane_b32 s22, v26, 41
	v_readlane_b32 s23, v27, 41
	v_readlane_b32 s24, v28, 41
	v_readlane_b32 s25, v29, 41
	v_readlane_b32 s26, v30, 41
	v_readlane_b32 s27, v31, 41
	v_readlane_b32 s30, v32, 41
	v_readlane_b32 s31, v33, 41
	s_waitcnt vmcnt(23)
	v_pk_fma_f32 v[16:17], v[120:121], s[6:7], v[16:17] op_sel_hi:[0,1,1]
	v_pk_fma_f32 v[14:15], v[120:121], s[8:9], v[14:15] op_sel_hi:[0,1,1]
	v_pk_fma_f32 v[12:13], v[120:121], s[10:11], v[12:13] op_sel_hi:[0,1,1]
	v_pk_fma_f32 v[10:11], v[120:121], s[12:13], v[10:11] op_sel_hi:[0,1,1]
	v_readlane_b32 s6, v26, 42
	v_readlane_b32 s7, v27, 42
	v_readlane_b32 s8, v28, 42
	v_readlane_b32 s9, v29, 42
	v_readlane_b32 s10, v30, 42
	v_readlane_b32 s11, v31, 42
	v_readlane_b32 s12, v32, 42
	v_readlane_b32 s13, v33, 42
	s_waitcnt vmcnt(22)
	v_pk_fma_f32 v[16:17], v[122:123], s[22:23], v[16:17] op_sel_hi:[0,1,1]
	v_pk_fma_f32 v[14:15], v[122:123], s[24:25], v[14:15] op_sel_hi:[0,1,1]
	v_pk_fma_f32 v[12:13], v[122:123], s[26:27], v[12:13] op_sel_hi:[0,1,1]
	v_pk_fma_f32 v[10:11], v[122:123], s[30:31], v[10:11] op_sel_hi:[0,1,1]
	v_readlane_b32 s22, v26, 43
	v_readlane_b32 s23, v27, 43
	v_readlane_b32 s24, v28, 43
	v_readlane_b32 s25, v29, 43
	v_readlane_b32 s26, v30, 43
	v_readlane_b32 s27, v31, 43
	v_readlane_b32 s30, v32, 43
	v_readlane_b32 s31, v33, 43
	s_waitcnt vmcnt(21)
	v_pk_fma_f32 v[16:17], v[124:125], s[6:7], v[16:17] op_sel_hi:[0,1,1]
	v_pk_fma_f32 v[14:15], v[124:125], s[8:9], v[14:15] op_sel_hi:[0,1,1]
	v_pk_fma_f32 v[12:13], v[124:125], s[10:11], v[12:13] op_sel_hi:[0,1,1]
	v_pk_fma_f32 v[10:11], v[124:125], s[12:13], v[10:11] op_sel_hi:[0,1,1]
	v_readlane_b32 s6, v26, 44
	v_readlane_b32 s7, v27, 44
	v_readlane_b32 s8, v28, 44
	v_readlane_b32 s9, v29, 44
	v_readlane_b32 s10, v30, 44
	v_readlane_b32 s11, v31, 44
	v_readlane_b32 s12, v32, 44
	v_readlane_b32 s13, v33, 44
	s_waitcnt vmcnt(20)
	v_pk_fma_f32 v[16:17], v[126:127], s[22:23], v[16:17] op_sel_hi:[0,1,1]
	v_pk_fma_f32 v[14:15], v[126:127], s[24:25], v[14:15] op_sel_hi:[0,1,1]
	v_pk_fma_f32 v[12:13], v[126:127], s[26:27], v[12:13] op_sel_hi:[0,1,1]
	v_pk_fma_f32 v[10:11], v[126:127], s[30:31], v[10:11] op_sel_hi:[0,1,1]
	v_readlane_b32 s22, v26, 45
	v_readlane_b32 s23, v27, 45
	v_readlane_b32 s24, v28, 45
	v_readlane_b32 s25, v29, 45
	v_readlane_b32 s26, v30, 45
	v_readlane_b32 s27, v31, 45
	v_readlane_b32 s30, v32, 45
	v_readlane_b32 s31, v33, 45
	s_waitcnt vmcnt(19)
	v_pk_fma_f32 v[16:17], v[128:129], s[6:7], v[16:17] op_sel_hi:[0,1,1]
	v_pk_fma_f32 v[14:15], v[128:129], s[8:9], v[14:15] op_sel_hi:[0,1,1]
	v_pk_fma_f32 v[12:13], v[128:129], s[10:11], v[12:13] op_sel_hi:[0,1,1]
	v_pk_fma_f32 v[10:11], v[128:129], s[12:13], v[10:11] op_sel_hi:[0,1,1]
	v_readlane_b32 s6, v26, 46
	v_readlane_b32 s7, v27, 46
	v_readlane_b32 s8, v28, 46
	v_readlane_b32 s9, v29, 46
	v_readlane_b32 s10, v30, 46
	v_readlane_b32 s11, v31, 46
	v_readlane_b32 s12, v32, 46
	v_readlane_b32 s13, v33, 46
	s_waitcnt vmcnt(18)
	v_pk_fma_f32 v[16:17], v[130:131], s[22:23], v[16:17] op_sel_hi:[0,1,1]
	v_pk_fma_f32 v[14:15], v[130:131], s[24:25], v[14:15] op_sel_hi:[0,1,1]
	v_pk_fma_f32 v[12:13], v[130:131], s[26:27], v[12:13] op_sel_hi:[0,1,1]
	v_pk_fma_f32 v[10:11], v[130:131], s[30:31], v[10:11] op_sel_hi:[0,1,1]
	v_readlane_b32 s22, v26, 47
	v_readlane_b32 s23, v27, 47
	v_readlane_b32 s24, v28, 47
	v_readlane_b32 s25, v29, 47
	v_readlane_b32 s26, v30, 47
	v_readlane_b32 s27, v31, 47
	v_readlane_b32 s30, v32, 47
	v_readlane_b32 s31, v33, 47
	s_waitcnt vmcnt(17)
	v_pk_fma_f32 v[16:17], v[132:133], s[6:7], v[16:17] op_sel_hi:[0,1,1]
	v_pk_fma_f32 v[14:15], v[132:133], s[8:9], v[14:15] op_sel_hi:[0,1,1]
	v_pk_fma_f32 v[12:13], v[132:133], s[10:11], v[12:13] op_sel_hi:[0,1,1]
	v_pk_fma_f32 v[10:11], v[132:133], s[12:13], v[10:11] op_sel_hi:[0,1,1]
	v_readlane_b32 s6, v26, 48
	v_readlane_b32 s7, v27, 48
	v_readlane_b32 s8, v28, 48
	v_readlane_b32 s9, v29, 48
	v_readlane_b32 s10, v30, 48
	v_readlane_b32 s11, v31, 48
	v_readlane_b32 s12, v32, 48
	v_readlane_b32 s13, v33, 48
	s_waitcnt vmcnt(16)
	v_pk_fma_f32 v[16:17], v[134:135], s[22:23], v[16:17] op_sel_hi:[0,1,1]
	v_pk_fma_f32 v[14:15], v[134:135], s[24:25], v[14:15] op_sel_hi:[0,1,1]
	v_pk_fma_f32 v[12:13], v[134:135], s[26:27], v[12:13] op_sel_hi:[0,1,1]
	v_pk_fma_f32 v[10:11], v[134:135], s[30:31], v[10:11] op_sel_hi:[0,1,1]
	v_readlane_b32 s22, v26, 49
	v_readlane_b32 s23, v27, 49
	v_readlane_b32 s24, v28, 49
	v_readlane_b32 s25, v29, 49
	v_readlane_b32 s26, v30, 49
	v_readlane_b32 s27, v31, 49
	v_readlane_b32 s30, v32, 49
	v_readlane_b32 s31, v33, 49
	s_waitcnt vmcnt(15)
	v_pk_fma_f32 v[16:17], v[136:137], s[6:7], v[16:17] op_sel_hi:[0,1,1]
	v_pk_fma_f32 v[14:15], v[136:137], s[8:9], v[14:15] op_sel_hi:[0,1,1]
	v_pk_fma_f32 v[12:13], v[136:137], s[10:11], v[12:13] op_sel_hi:[0,1,1]
	v_pk_fma_f32 v[10:11], v[136:137], s[12:13], v[10:11] op_sel_hi:[0,1,1]
	v_readlane_b32 s6, v26, 50
	v_readlane_b32 s7, v27, 50
	v_readlane_b32 s8, v28, 50
	v_readlane_b32 s9, v29, 50
	v_readlane_b32 s10, v30, 50
	v_readlane_b32 s11, v31, 50
	v_readlane_b32 s12, v32, 50
	v_readlane_b32 s13, v33, 50
	s_waitcnt vmcnt(14)
	v_pk_fma_f32 v[16:17], v[138:139], s[22:23], v[16:17] op_sel_hi:[0,1,1]
	v_pk_fma_f32 v[14:15], v[138:139], s[24:25], v[14:15] op_sel_hi:[0,1,1]
	v_pk_fma_f32 v[12:13], v[138:139], s[26:27], v[12:13] op_sel_hi:[0,1,1]
	v_pk_fma_f32 v[10:11], v[138:139], s[30:31], v[10:11] op_sel_hi:[0,1,1]
	v_readlane_b32 s22, v26, 51
	v_readlane_b32 s23, v27, 51
	v_readlane_b32 s24, v28, 51
	v_readlane_b32 s25, v29, 51
	v_readlane_b32 s26, v30, 51
	v_readlane_b32 s27, v31, 51
	v_readlane_b32 s30, v32, 51
	v_readlane_b32 s31, v33, 51
	s_waitcnt vmcnt(13)
	v_pk_fma_f32 v[16:17], v[140:141], s[6:7], v[16:17] op_sel_hi:[0,1,1]
	v_pk_fma_f32 v[14:15], v[140:141], s[8:9], v[14:15] op_sel_hi:[0,1,1]
	v_pk_fma_f32 v[12:13], v[140:141], s[10:11], v[12:13] op_sel_hi:[0,1,1]
	v_pk_fma_f32 v[10:11], v[140:141], s[12:13], v[10:11] op_sel_hi:[0,1,1]
	v_readlane_b32 s6, v26, 52
	v_readlane_b32 s7, v27, 52
	v_readlane_b32 s8, v28, 52
	v_readlane_b32 s9, v29, 52
	v_readlane_b32 s10, v30, 52
	v_readlane_b32 s11, v31, 52
	v_readlane_b32 s12, v32, 52
	v_readlane_b32 s13, v33, 52
	s_waitcnt vmcnt(12)
	v_pk_fma_f32 v[16:17], v[142:143], s[22:23], v[16:17] op_sel_hi:[0,1,1]
	v_pk_fma_f32 v[14:15], v[142:143], s[24:25], v[14:15] op_sel_hi:[0,1,1]
	v_pk_fma_f32 v[12:13], v[142:143], s[26:27], v[12:13] op_sel_hi:[0,1,1]
	v_pk_fma_f32 v[10:11], v[142:143], s[30:31], v[10:11] op_sel_hi:[0,1,1]
	v_readlane_b32 s22, v26, 53
	v_readlane_b32 s23, v27, 53
	v_readlane_b32 s24, v28, 53
	v_readlane_b32 s25, v29, 53
	v_readlane_b32 s26, v30, 53
	v_readlane_b32 s27, v31, 53
	v_readlane_b32 s30, v32, 53
	v_readlane_b32 s31, v33, 53
	s_waitcnt vmcnt(11)
	v_pk_fma_f32 v[16:17], v[144:145], s[6:7], v[16:17] op_sel_hi:[0,1,1]
	v_pk_fma_f32 v[14:15], v[144:145], s[8:9], v[14:15] op_sel_hi:[0,1,1]
	v_pk_fma_f32 v[12:13], v[144:145], s[10:11], v[12:13] op_sel_hi:[0,1,1]
	v_pk_fma_f32 v[10:11], v[144:145], s[12:13], v[10:11] op_sel_hi:[0,1,1]
	v_readlane_b32 s6, v26, 54
	v_readlane_b32 s7, v27, 54
	v_readlane_b32 s8, v28, 54
	v_readlane_b32 s9, v29, 54
	v_readlane_b32 s10, v30, 54
	v_readlane_b32 s11, v31, 54
	v_readlane_b32 s12, v32, 54
	v_readlane_b32 s13, v33, 54
	s_waitcnt vmcnt(10)
	v_pk_fma_f32 v[16:17], v[146:147], s[22:23], v[16:17] op_sel_hi:[0,1,1]
	v_pk_fma_f32 v[14:15], v[146:147], s[24:25], v[14:15] op_sel_hi:[0,1,1]
	v_pk_fma_f32 v[12:13], v[146:147], s[26:27], v[12:13] op_sel_hi:[0,1,1]
	v_pk_fma_f32 v[10:11], v[146:147], s[30:31], v[10:11] op_sel_hi:[0,1,1]
	v_readlane_b32 s22, v26, 55
	v_readlane_b32 s23, v27, 55
	v_readlane_b32 s24, v28, 55
	v_readlane_b32 s25, v29, 55
	v_readlane_b32 s26, v30, 55
	v_readlane_b32 s27, v31, 55
	v_readlane_b32 s30, v32, 55
	v_readlane_b32 s31, v33, 55
	s_waitcnt vmcnt(9)
	v_pk_fma_f32 v[16:17], v[148:149], s[6:7], v[16:17] op_sel_hi:[0,1,1]
	v_pk_fma_f32 v[14:15], v[148:149], s[8:9], v[14:15] op_sel_hi:[0,1,1]
	v_pk_fma_f32 v[12:13], v[148:149], s[10:11], v[12:13] op_sel_hi:[0,1,1]
	v_pk_fma_f32 v[10:11], v[148:149], s[12:13], v[10:11] op_sel_hi:[0,1,1]
	v_readlane_b32 s6, v26, 56
	v_readlane_b32 s7, v27, 56
	v_readlane_b32 s8, v28, 56
	v_readlane_b32 s9, v29, 56
	v_readlane_b32 s10, v30, 56
	v_readlane_b32 s11, v31, 56
	v_readlane_b32 s12, v32, 56
	v_readlane_b32 s13, v33, 56
	s_waitcnt vmcnt(8)
	v_pk_fma_f32 v[16:17], v[150:151], s[22:23], v[16:17] op_sel_hi:[0,1,1]
	v_pk_fma_f32 v[14:15], v[150:151], s[24:25], v[14:15] op_sel_hi:[0,1,1]
	v_pk_fma_f32 v[12:13], v[150:151], s[26:27], v[12:13] op_sel_hi:[0,1,1]
	v_pk_fma_f32 v[10:11], v[150:151], s[30:31], v[10:11] op_sel_hi:[0,1,1]
	v_readlane_b32 s22, v26, 57
	v_readlane_b32 s23, v27, 57
	v_readlane_b32 s24, v28, 57
	v_readlane_b32 s25, v29, 57
	v_readlane_b32 s26, v30, 57
	v_readlane_b32 s27, v31, 57
	v_readlane_b32 s30, v32, 57
	v_readlane_b32 s31, v33, 57
	s_waitcnt vmcnt(7)
	v_pk_fma_f32 v[16:17], v[152:153], s[6:7], v[16:17] op_sel_hi:[0,1,1]
	v_pk_fma_f32 v[14:15], v[152:153], s[8:9], v[14:15] op_sel_hi:[0,1,1]
	v_pk_fma_f32 v[12:13], v[152:153], s[10:11], v[12:13] op_sel_hi:[0,1,1]
	v_pk_fma_f32 v[10:11], v[152:153], s[12:13], v[10:11] op_sel_hi:[0,1,1]
	v_readlane_b32 s6, v26, 58
	v_readlane_b32 s7, v27, 58
	v_readlane_b32 s8, v28, 58
	v_readlane_b32 s9, v29, 58
	v_readlane_b32 s10, v30, 58
	v_readlane_b32 s11, v31, 58
	v_readlane_b32 s12, v32, 58
	v_readlane_b32 s13, v33, 58
	s_waitcnt vmcnt(6)
	v_pk_fma_f32 v[16:17], v[154:155], s[22:23], v[16:17] op_sel_hi:[0,1,1]
	v_pk_fma_f32 v[14:15], v[154:155], s[24:25], v[14:15] op_sel_hi:[0,1,1]
	v_pk_fma_f32 v[12:13], v[154:155], s[26:27], v[12:13] op_sel_hi:[0,1,1]
	v_pk_fma_f32 v[10:11], v[154:155], s[30:31], v[10:11] op_sel_hi:[0,1,1]
	v_readlane_b32 s22, v26, 59
	v_readlane_b32 s23, v27, 59
	v_readlane_b32 s24, v28, 59
	v_readlane_b32 s25, v29, 59
	v_readlane_b32 s26, v30, 59
	v_readlane_b32 s27, v31, 59
	v_readlane_b32 s30, v32, 59
	v_readlane_b32 s31, v33, 59
	s_waitcnt vmcnt(5)
	v_pk_fma_f32 v[16:17], v[156:157], s[6:7], v[16:17] op_sel_hi:[0,1,1]
	v_pk_fma_f32 v[14:15], v[156:157], s[8:9], v[14:15] op_sel_hi:[0,1,1]
	v_pk_fma_f32 v[12:13], v[156:157], s[10:11], v[12:13] op_sel_hi:[0,1,1]
	v_pk_fma_f32 v[10:11], v[156:157], s[12:13], v[10:11] op_sel_hi:[0,1,1]
	v_readlane_b32 s6, v26, 60
	v_readlane_b32 s7, v27, 60
	v_readlane_b32 s8, v28, 60
	v_readlane_b32 s9, v29, 60
	v_readlane_b32 s10, v30, 60
	v_readlane_b32 s11, v31, 60
	v_readlane_b32 s12, v32, 60
	v_readlane_b32 s13, v33, 60
	s_waitcnt vmcnt(4)
	v_pk_fma_f32 v[16:17], v[158:159], s[22:23], v[16:17] op_sel_hi:[0,1,1]
	v_pk_fma_f32 v[14:15], v[158:159], s[24:25], v[14:15] op_sel_hi:[0,1,1]
	v_pk_fma_f32 v[12:13], v[158:159], s[26:27], v[12:13] op_sel_hi:[0,1,1]
	v_pk_fma_f32 v[10:11], v[158:159], s[30:31], v[10:11] op_sel_hi:[0,1,1]
	v_readlane_b32 s22, v26, 61
	v_readlane_b32 s23, v27, 61
	v_readlane_b32 s24, v28, 61
	v_readlane_b32 s25, v29, 61
	v_readlane_b32 s26, v30, 61
	v_readlane_b32 s27, v31, 61
	v_readlane_b32 s30, v32, 61
	v_readlane_b32 s31, v33, 61
	s_waitcnt vmcnt(3)
	v_pk_fma_f32 v[16:17], v[164:165], s[6:7], v[16:17] op_sel_hi:[0,1,1]
	v_pk_fma_f32 v[14:15], v[164:165], s[8:9], v[14:15] op_sel_hi:[0,1,1]
	v_pk_fma_f32 v[12:13], v[164:165], s[10:11], v[12:13] op_sel_hi:[0,1,1]
	v_pk_fma_f32 v[10:11], v[164:165], s[12:13], v[10:11] op_sel_hi:[0,1,1]
	v_readlane_b32 s6, v26, 62
	v_readlane_b32 s7, v27, 62
	v_readlane_b32 s8, v28, 62
	v_readlane_b32 s9, v29, 62
	v_readlane_b32 s10, v30, 62
	v_readlane_b32 s11, v31, 62
	v_readlane_b32 s12, v32, 62
	v_readlane_b32 s13, v33, 62
	s_waitcnt vmcnt(2)
	v_pk_fma_f32 v[16:17], v[166:167], s[22:23], v[16:17] op_sel_hi:[0,1,1]
	v_pk_fma_f32 v[14:15], v[166:167], s[24:25], v[14:15] op_sel_hi:[0,1,1]
	v_pk_fma_f32 v[12:13], v[166:167], s[26:27], v[12:13] op_sel_hi:[0,1,1]
	v_pk_fma_f32 v[10:11], v[166:167], s[30:31], v[10:11] op_sel_hi:[0,1,1]
	v_readlane_b32 s22, v26, 63
	v_readlane_b32 s23, v27, 63
	v_readlane_b32 s24, v28, 63
	v_readlane_b32 s25, v29, 63
	v_readlane_b32 s26, v30, 63
	v_readlane_b32 s27, v31, 63
	v_readlane_b32 s30, v32, 63
	v_readlane_b32 s31, v33, 63
	s_waitcnt vmcnt(1)
	v_pk_fma_f32 v[16:17], v[168:169], s[6:7], v[16:17] op_sel_hi:[0,1,1]
	v_pk_fma_f32 v[14:15], v[168:169], s[8:9], v[14:15] op_sel_hi:[0,1,1]
	v_pk_fma_f32 v[12:13], v[168:169], s[10:11], v[12:13] op_sel_hi:[0,1,1]
	v_pk_fma_f32 v[10:11], v[168:169], s[12:13], v[10:11] op_sel_hi:[0,1,1]
	s_waitcnt vmcnt(0)
	v_pk_fma_f32 v[16:17], v[170:171], s[22:23], v[16:17] op_sel_hi:[0,1,1]
	v_pk_fma_f32 v[14:15], v[170:171], s[24:25], v[14:15] op_sel_hi:[0,1,1]
	v_pk_fma_f32 v[12:13], v[170:171], s[26:27], v[12:13] op_sel_hi:[0,1,1]
	v_pk_fma_f32 v[10:11], v[170:171], s[30:31], v[10:11] op_sel_hi:[0,1,1]
	s_lshl_b32 s0, s2, 6
	s_and_b32 s0, s0, 0x7c0
	v_or_b32_e32 v3, s0, v2
	v_readlane_b32 s0, v251, 24
	v_lshlrev_b32_e32 v4, 2, v3
	v_mov_b32_e32 v5, v1
	v_readlane_b32 s1, v251, 25
	s_lshl_b32 s90, s4, 13
	s_nop 0
	v_lshl_add_u64 v[4:5], s[0:1], 0, v[4:5]
	v_lshl_add_u64 v[4:5], v[4:5], 0, s[90:91]
	v_add_co_u32_e32 v6, vcc, 0x2000, v4
	global_atomic_add_f32 v[4:5], v16, off
	s_nop 0
	v_addc_co_u32_e32 v7, vcc, 0, v5, vcc
	global_atomic_add_f32 v[6:7], v17, off
	v_add_co_u32_e32 v6, vcc, 0x4000, v4
	v_readlane_b32 s0, v254, 6
	s_nop 0
	v_addc_co_u32_e32 v7, vcc, 0, v5, vcc
	global_atomic_add_f32 v[6:7], v14, off
	v_add_co_u32_e32 v6, vcc, 0x6000, v4
	v_readlane_b32 s1, v254, 7
	s_nop 0
	v_addc_co_u32_e32 v7, vcc, 0, v5, vcc
	global_atomic_add_f32 v[6:7], v15, off
	v_add_co_u32_e32 v6, vcc, 0x8000, v4
	s_addk_i32 s2, 0x600
	s_nop 0
	v_addc_co_u32_e32 v7, vcc, 0, v5, vcc
	global_atomic_add_f32 v[6:7], v12, off
	v_add_co_u32_e32 v6, vcc, 0xa000, v4
	v_readlane_b32 s0, v254, 2
	s_nop 0
	v_addc_co_u32_e32 v7, vcc, 0, v5, vcc
	global_atomic_add_f32 v[6:7], v13, off
	v_add_co_u32_e32 v6, vcc, 0xc000, v4
	s_add_i32 s3, s3, 0x18000
	s_nop 0
	v_addc_co_u32_e32 v7, vcc, 0, v5, vcc
	v_add_co_u32_e32 v4, vcc, 0xe000, v4
	global_atomic_add_f32 v[6:7], v10, off
	s_nop 0
	v_addc_co_u32_e32 v5, vcc, 0, v5, vcc
	global_atomic_add_f32 v[4:5], v11, off
	s_cmpk_gt_i32 s2, 0xfff
	v_readlane_b32 s1, v254, 3
	s_cbranch_scc0 .LBB0_830
